# post phase removed: its rows (prompt and sample) are post-processed inside the scan/attention phase, x_sample copy and new_v outputs moved to wave 5, one grid barrier less
# speedup vs baseline: 1.0994x; 1.0063x over previous
.LBB0_6:
	s_mov_b32 s27, 11
	s_add_u32 s12, s24, 0x8a19c00
	s_addc_u32 s13, s25, 0
	s_add_u32 s34, s24, 0x3400000
	s_addc_u32 s35, s25, 0
	s_add_u32 s54, s24, 0x4f00000
	s_addc_u32 s55, s25, 0
	s_add_u32 s96, s24, 0x152b7000
	s_addc_u32 s97, s25, 0
	s_cmpk_lg_i32 s52, 0x100
	s_cselect_b64 s[4:5], -1, 0
	v_writelane_b32 v250, s4, 2
	s_ashr_i32 s36, s68, 3
	s_load_dwordx16 s[80:95], s[0:1], 0x80
	v_writelane_b32 v250, s5, 3
	s_lshl_b32 s4, s68, 5
	s_and_b32 s4, s4, 0xe0
	s_add_i32 s39, s4, s36
	s_cmpk_eq_i32 s52, 0x100
	s_cselect_b64 s[4:5], -1, 0
	v_writelane_b32 v250, s4, 4
	v_mbcnt_lo_u32_b32 v2, -1, 0
	v_mbcnt_hi_u32_b32 v163, -1, v2
	v_writelane_b32 v250, s5, 5
	s_and_b64 s[4:5], s[4:5], exec
	s_cselect_b32 s33, s39, s68
	s_movk_i32 s4, 0x300
	s_cselect_b32 s46, s4, 0x339
	s_cmpk_lt_i32 s33, 0x1b0
	s_cselect_b64 s[4:5], -1, 0
	v_writelane_b32 v250, s4, 6
	s_cmpk_lt_i32 s33, 0x100
	v_mov_b32_e32 v158, 0x358637bd
	v_writelane_b32 v250, s5, 7
	s_cselect_b64 s[4:5], -1, 0
	s_and_b32 s15, s33, 7
	s_bfe_u32 s6, s33, 0x50003
	s_add_u32 s7, s24, 0x13a19c00
	s_addc_u32 s8, s25, 0
	s_lshl_b32 s31, s6, 9
	s_add_u32 s14, s7, s31
	v_writelane_b32 v250, s6, 8
	s_mul_i32 s6, s15, 0x2c0000
	s_addc_u32 s16, s8, 0
	s_add_u32 s6, s34, s6
	v_writelane_b32 v250, s7, 9
	s_addc_u32 s7, s35, 0
	s_add_u32 s17, s6, s31
	s_addc_u32 s18, s7, 0
	s_ashr_i32 s6, s33, 31
	s_lshr_b32 s6, s6, 27
	s_add_i32 s6, s33, s6
	s_ashr_i32 s7, s6, 5
	s_andn2_b32 s6, s6, 31
	s_sub_i32 s6, s33, s6
	v_writelane_b32 v250, s8, 10
	s_ashr_i32 s8, s6, 31
	s_lshr_b32 s8, s8, 30
	s_lshl_b32 s7, s7, 2
	s_add_i32 s9, s6, s8
	s_add_i32 s6, s6, s7
	s_and_b32 s7, s9, -4
	s_sub_i32 s6, s6, s7
	s_ashr_i32 s8, s9, 2
	s_ashr_i32 s7, s6, 31
	s_mul_i32 s11, s6, 0x580000
	s_mul_hi_i32 s9, s6, 0x580000
	s_add_u32 s19, s12, s11
	v_writelane_b32 v250, s12, 11
	s_addc_u32 s29, s13, s9
	s_ashr_i32 s9, s8, 31
	s_mul_i32 s12, s8, 0x2c0000
	v_writelane_b32 v250, s13, 12
	s_mul_hi_i32 s11, s8, 0x2c0000
	s_add_u32 s57, s34, s12
	v_writelane_b32 v250, s34, 13
	s_addc_u32 s30, s35, s11
	s_lshl_b32 s11, s68, 9
	s_lshl_b32 s28, s52, 9
	s_add_u32 vcc_lo, s24, 0x8a17000
	s_addc_u32 vcc_hi, s25, 0
	s_add_u32 s48, s24, 0x6917000
	s_addc_u32 s49, s25, 0
	s_add_u32 s50, s24, 0x800000
	s_addc_u32 s51, s25, 0
	v_writelane_b32 v250, s35, 14
	s_cmpk_lt_i32 s33, 0x5ac
	v_writelane_b32 v250, s11, 15
	s_cselect_b64 s[12:13], -1, 0
	v_writelane_b32 v250, s12, 16
	s_mul_hi_i32 s11, s33, 0x2e8ba2e9
	v_mov_b32_e32 v202, 0x260
	v_writelane_b32 v250, s13, 17
	s_lshr_b32 s12, s11, 31
	s_ashr_i32 s11, s11, 5
	s_add_i32 s11, s11, s12
	s_mul_i32 s13, s11, 0xffffff50
	s_lshl_b32 s12, s11, 2
	s_sub_i32 s11, 33, s12
	s_add_i32 s13, s13, s33
	s_min_u32 s11, s11, 4
	s_add_i32 s12, s13, s12
	s_cmpk_lt_i32 s68, 0x108
	s_cselect_b64 s[34:35], -1, 0
	s_add_u32 s70, s24, 0x5017000
	s_addc_u32 s71, s25, 0
	v_writelane_b32 v250, s34, 18
	s_cmpk_lt_i32 s33, 0x140
	v_cvt_f32_ubyte0_e32 v1, s11
	v_writelane_b32 v250, s35, 19
	s_cselect_b64 s[34:35], -1, 0
	v_writelane_b32 v250, s34, 20
	v_rcp_iflag_f32_e32 v1, v1
	v_mov_b32_e32 v160, 1.0
	v_writelane_b32 v250, s35, 21
	s_add_u32 s34, s24, 0x7017000
	s_addc_u32 s35, s25, 0
	s_add_u32 s37, s34, s31
	v_writelane_b32 v250, s34, 22
	s_addc_u32 s38, s35, 0
	s_lshl_b32 s34, s15, 20
	s_add_u32 s34, s24, s34
	v_writelane_b32 v250, s35, 23
	s_addc_u32 s35, s25, 0
	s_add_u32 s41, s34, s31
	s_addc_u32 s43, s35, 0
	s_lshl_b64 s[34:35], s[6:7], 20
	s_add_u32 s40, s70, s34
	s_addc_u32 s42, s71, s35
	s_lshl_b64 s[34:35], s[8:9], 20
	s_add_u32 s44, s24, s34
	s_addc_u32 s45, s25, s35
	s_add_u32 s72, s24, 0xbb97000
	s_addc_u32 s73, s25, 0
	s_add_u32 s34, s24, 0x172f7000
	s_addc_u32 s35, s25, 0
	v_writelane_b32 v250, s34, 24
	v_mul_f32_e32 v1, 0x4f7ffffe, v1
	v_cvt_u32_f32_e32 v1, v1
	v_writelane_b32 v250, s35, 25
	s_add_u32 s34, s24, 0x4f90000
	s_addc_u32 s35, s25, 0
	s_lshl_b32 s47, s68, 3
	s_lshl_b32 s56, s52, 3
	s_add_u32 s64, s22, 0x4000000
	v_writelane_b32 v250, s34, 26
	s_addc_u32 s65, s23, 0
	v_mov_b32_e32 v203, 1
	v_writelane_b32 v250, s35, 27
	s_add_u32 s34, s24, 0xab17000
	s_addc_u32 s35, s25, 0
	v_writelane_b32 v250, s34, 28
	v_mov_b32_e32 v204, 0x7fe
	v_mov_b32_e32 v205, 0x520d000
	v_writelane_b32 v250, s35, 29
	s_add_u32 s34, s22, 0x52b9000
	s_addc_u32 s35, s23, 0
	v_writelane_b32 v250, s34, 30
	v_mov_b32_e32 v206, 0x5553000
	v_mov_b32_e32 v207, 0x1800
	v_writelane_b32 v250, s35, 31
	s_add_u32 s34, s22, 0x4900000
	s_addc_u32 s35, s23, 0
	v_writelane_b32 v250, s34, 32
	s_cmpk_lt_i32 s68, 0x300
	v_mov_b32_e32 v208, 0xfffff800
	v_writelane_b32 v250, s35, 33
	s_cselect_b64 s[34:35], -1, 0
	s_add_u32 s66, s24, 0x111b7000
	s_addc_u32 s67, s25, 0
	s_add_u32 s58, s24, 0xf137000
	v_writelane_b32 v250, s34, 34
	s_addc_u32 s59, s25, 0
	s_add_u32 s7, s22, 0x5339000
	v_writelane_b32 v250, s35, 35
	v_writelane_b32 v250, s7, 36
	s_addc_u32 s7, s23, 0
	v_writelane_b32 v250, s7, 37
	s_add_u32 s7, s22, 0x5100000
	v_writelane_b32 v250, s7, 38
	s_addc_u32 s7, s23, 0
	v_writelane_b32 v250, s7, 39
	s_add_u32 s7, s24, 0x5012200
	v_writelane_b32 v250, s7, 40
	s_addc_u32 s7, s25, 0
	s_add_u32 s34, s24, 0x16af7000
	s_addc_u32 s35, s25, 0
	s_cmp_eq_u32 s68, 0
	v_writelane_b32 v250, s7, 41
	s_cselect_b64 s[74:75], -1, 0
	v_writelane_b32 v250, s74, 42
	v_mov_b32_e32 v162, 0x3a27c5ac
	v_mov_b32_e32 v214, 0x80
	v_writelane_b32 v250, s75, 43
	s_add_u32 s74, s24, 0x5012000
	s_addc_u32 s75, s25, 0
	s_add_i32 s7, s39, 0x300
	v_writelane_b32 v250, s74, 44
	s_cmp_lt_i32 s39, 57
	v_mov_b32_e32 v215, 0x1000000
	v_writelane_b32 v250, s75, 45
	s_cselect_b64 s[74:75], -1, 0
	v_writelane_b32 v250, s74, 46
	s_cmpk_lt_i32 s39, 0xffb5
	v_mov_b64_e32 v[164:165], 0x16af7000
	v_writelane_b32 v250, s75, 47
	s_cselect_b64 s[74:75], -1, 0
	s_add_i32 s9, s39, 0x4b
	v_writelane_b32 v250, s74, 48
	s_and_b32 s31, s9, 3
	v_mov_b32_e32 v216, 0xf149f2ca
	v_writelane_b32 v250, s75, 49
	s_lshr_b32 s74, s9, 2
	s_lshl_b32 s9, s31, 20
	v_writelane_b32 v250, s39, 50
	s_add_u32 s9, s70, s9
	v_writelane_b32 v250, s31, 51
	s_addc_u32 s31, s71, 0
	s_add_u32 s76, s9, 0x800000
	s_mul_hi_i32 s9, s7, 0x30c30c31
	s_addc_u32 s77, s31, 0
	s_lshr_b32 s31, s9, 31
	s_ashr_i32 s9, s9, 4
	s_add_i32 s9, s9, s31
	v_writelane_b32 v250, s76, 52
	s_mul_i32 s31, s9, 0xffffffac
	s_lshl_b32 s9, s9, 2
	s_add_i32 s36, s36, -1
	v_writelane_b32 v250, s77, 53
	s_add_i32 s31, s31, s7
	s_sub_i32 s7, 33, s9
	s_and_b32 s36, s36, 3
	s_min_u32 s7, s7, 4
	s_add_i32 s9, s31, s9
	v_writelane_b32 v250, s36, 54
	s_lshl_b32 s36, s36, 20
	s_add_u32 s36, s70, s36
	s_addc_u32 s39, s71, 0
	s_add_u32 s76, s36, 0x800000
	s_addc_u32 s77, s39, 0
	v_writelane_b32 v250, s76, 55
	v_mov_b32_e32 v217, -4
	v_mov_b32_e32 v218, 0x200f
	v_writelane_b32 v250, s77, 56
	s_add_u32 s76, s22, 0x4100000
	s_addc_u32 s77, s23, 0
	v_writelane_b32 v250, s76, 57
	v_mov_b32_e32 v219, 0x41b17218
	v_mov_b32_e32 v222, 0xfff3a000
	v_writelane_b32 v250, s77, 58
	s_add_u32 s76, s22, 0x5239000
	s_addc_u32 s77, s23, 0
	v_writelane_b32 v250, s76, 59
	s_ashr_i32 s69, s68, 31
	s_ashr_i32 s53, s52, 31
	v_writelane_b32 v250, s77, 60
	s_lshl_b64 s[76:77], s[68:69], 9
	v_writelane_b32 v250, s76, 61
	v_mov_b32_e32 v223, 6
	s_movk_i32 s69, 0x5ff
	v_writelane_b32 v250, s77, 62
	s_lshl_b64 s[76:77], s[52:53], 9
	s_add_u32 s78, s24, 0x4a00000
	v_writelane_b32 v250, s76, 63
	s_addc_u32 s79, s25, 0
	s_nop 0
	v_writelane_b32 v251, s77, 0
	s_add_u32 s76, s24, 0x5012100
	s_addc_u32 s77, s25, 0
	v_writelane_b32 v251, s76, 1
	s_waitcnt lgkmcnt(0)
	s_add_u32 s60, s82, 0x3000
	v_writelane_b32 v251, s77, 2
	v_writelane_b32 v251, s80, 3
	s_addc_u32 s61, s83, 0
	s_cmp_lt_i32 s33, s46
	v_writelane_b32 v251, s81, 4
	v_writelane_b32 v251, s82, 5
	v_writelane_b32 v251, s83, 6
	v_writelane_b32 v251, s84, 7
	v_writelane_b32 v251, s85, 8
	v_writelane_b32 v251, s86, 9
	v_writelane_b32 v251, s87, 10
	v_writelane_b32 v251, s88, 11
	v_writelane_b32 v251, s89, 12
	v_writelane_b32 v251, s90, 13
	v_writelane_b32 v251, s91, 14
	v_writelane_b32 v251, s92, 15
	v_writelane_b32 v251, s93, 16
	v_writelane_b32 v251, s94, 17
	v_writelane_b32 v251, s95, 18
	v_writelane_b32 v251, s60, 19
	s_mov_b64 s[90:91], s[54:55]
	s_mov_b32 s88, s52
	v_writelane_b32 v251, s61, 20
	v_writelane_b32 v251, s46, 21
	s_cselect_b64 s[60:61], -1, 0
	v_writelane_b32 v251, s60, 22
	s_cmpk_lt_i32 s33, 0x2b5
	s_movk_i32 s93, 0x210
	v_writelane_b32 v251, s61, 23
	s_cselect_b64 s[60:61], -1, 0
	s_add_i32 s36, s33, 0xfffffd4b
	v_writelane_b32 v251, s60, 24
	s_and_b32 s39, s36, 3
	s_mov_b64 s[94:95], 0x80
	v_writelane_b32 v251, s61, 25
	s_lshr_b32 s60, s36, 2
	s_lshl_b32 s36, s39, 20
	s_add_u32 s36, s70, s36
	v_writelane_b32 v251, s39, 26
	s_addc_u32 s39, s71, 0
	s_add_u32 s62, s36, 0x800000
	s_mul_hi_i32 s36, s33, 0x30c30c31
	s_addc_u32 s63, s39, 0
	s_lshr_b32 s39, s36, 31
	s_ashr_i32 s36, s36, 4
	s_add_i32 s36, s36, s39
	s_mul_i32 s39, s36, 0xffffffac
	s_lshl_b32 s36, s36, 2
	s_add_i32 s39, s39, s33
	s_sub_i32 s33, 33, s36
	v_writelane_b32 v251, s62, 27
	s_min_u32 s33, s33, 4
	s_add_i32 s36, s39, s36
	v_writelane_b32 v251, s63, 28
	s_add_u32 s62, s24, 0x4a80000
	s_addc_u32 s63, s25, 0
	v_writelane_b32 v251, s62, 29
	s_cmp_lt_i32 s68, 12
	s_mov_b32 s92, 0x3e027906
	v_writelane_b32 v251, s63, 30
	s_cselect_b64 s[62:63], -1, 0
	v_writelane_b32 v251, s62, 31
	s_cmpk_lt_i32 s68, 0x180
	s_nop 0
	v_writelane_b32 v251, s63, 32
	s_cselect_b64 s[62:63], -1, 0
	v_writelane_b32 v251, s62, 33
	s_nop 1
	v_writelane_b32 v251, s63, 34
	s_add_u32 s62, s24, 0x4a00100
	s_addc_u32 s63, s25, 0
	v_writelane_b32 v251, s62, 35
	s_nop 1
	v_writelane_b32 v251, s63, 36
	s_add_u32 s62, s24, 0x4a00080
	s_addc_u32 s63, s25, 0
	v_writelane_b32 v251, s62, 37
	s_cmp_lt_i32 s27, 0
	s_nop 0
	v_writelane_b32 v251, s63, 38
	s_cselect_b64 s[62:63], -1, 0
	v_writelane_b32 v251, s62, 39
	s_nop 1
	v_writelane_b32 v251, s63, 40
	s_add_u32 s62, s24, 0x5013200
	s_addc_u32 s63, s25, 0
	v_writelane_b32 v251, s62, 41
	s_nop 1
	v_writelane_b32 v251, s63, 42
	s_add_u32 s62, s24, 0x5013400
	s_addc_u32 s63, s25, 0
	v_writelane_b32 v251, s62, 43
	s_nop 1
	v_writelane_b32 v251, s63, 44
	s_add_u32 s62, s24, 0x5013500
	s_addc_u32 s63, s25, 0
	v_writelane_b32 v251, s62, 45
	s_nop 1
	v_writelane_b32 v251, s63, 46
	s_add_u32 s62, s24, 0x5013600
	s_addc_u32 s63, s25, 0
	v_writelane_b32 v251, s62, 47
	s_nop 1
	v_writelane_b32 v251, s63, 48
	s_add_u32 s62, s24, 0x5013700
	s_addc_u32 s63, s25, 0
	v_writelane_b32 v251, s62, 49
	s_nop 1
	v_writelane_b32 v251, s63, 50
	s_add_u32 s62, s24, 0x5013800
	s_addc_u32 s63, s25, 0
	v_writelane_b32 v251, s62, 51
	s_nop 1
	v_writelane_b32 v251, s63, 52
	s_add_u32 s62, s24, 0x5013900
	s_addc_u32 s63, s25, 0
	v_writelane_b32 v251, s62, 53
	s_nop 1
	v_writelane_b32 v251, s63, 54
	s_add_u32 s62, s24, 0x5013a00
	s_addc_u32 s63, s25, 0
	v_writelane_b32 v251, s62, 55
	s_nop 1
	v_writelane_b32 v251, s63, 56
	s_add_u32 s62, s24, 0x5013b00
	s_addc_u32 s63, s25, 0
	v_writelane_b32 v251, s62, 57
	s_nop 1
	v_writelane_b32 v251, s63, 58
	s_add_u32 s62, s24, 0x5013c00
	s_addc_u32 s63, s25, 0
	v_writelane_b32 v251, s62, 59
	s_nop 1
	v_writelane_b32 v251, s63, 60
	s_add_u32 s62, s24, 0x5013d00
	s_addc_u32 s63, s25, 0
	v_writelane_b32 v251, s62, 61
	s_nop 1
	v_writelane_b32 v251, s63, 62
	s_add_u32 s62, s24, 0x5013e00
	s_addc_u32 s63, s25, 0
	v_writelane_b32 v251, s62, 63
	s_nop 1
	v_writelane_b32 v252, s63, 0
	s_add_u32 s62, s24, 0x5013f00
	s_addc_u32 s63, s25, 0
	v_writelane_b32 v252, s62, 1
	s_nop 1
	v_writelane_b32 v252, s63, 2
	s_add_u32 s62, s24, 0x5014000
	s_addc_u32 s63, s25, 0
	v_writelane_b32 v252, s62, 3
	s_nop 1
	v_writelane_b32 v252, s63, 4
	s_add_u32 s62, s24, 0x5014100
	s_addc_u32 s63, s25, 0
	v_writelane_b32 v252, s62, 5
	s_nop 1
	v_writelane_b32 v252, s63, 6
	s_add_u32 s62, s24, 0x5014200
	s_addc_u32 s63, s25, 0
	v_writelane_b32 v252, s62, 7
	s_nop 1
	v_writelane_b32 v252, s63, 8
	s_add_u32 s62, s24, 0x5014300
	s_addc_u32 s63, s25, 0
	v_writelane_b32 v252, s62, 9
	s_cmp_eq_u32 s10, 15
	s_nop 0
	v_writelane_b32 v252, s63, 10
	s_cselect_b64 s[62:63], -1, 0
	v_writelane_b32 v252, s62, 11
	s_cmp_eq_u32 s10, 14
	s_nop 0
	v_writelane_b32 v252, s63, 12
	s_cselect_b64 s[62:63], -1, 0
	v_writelane_b32 v252, s62, 13
	s_cmp_eq_u32 s10, 13
	s_nop 0
	v_writelane_b32 v252, s63, 14
	s_cselect_b64 s[62:63], -1, 0
	v_writelane_b32 v252, s62, 15
	s_cmp_eq_u32 s10, 12
	s_nop 0
	v_writelane_b32 v252, s63, 16
	s_cselect_b64 s[62:63], -1, 0
	v_writelane_b32 v252, s62, 17
	s_cmp_eq_u32 s10, 11
	s_nop 0
	v_writelane_b32 v252, s63, 18
	s_cselect_b64 s[62:63], -1, 0
	v_writelane_b32 v252, s62, 19
	s_cmp_eq_u32 s10, 10
	s_nop 0
	v_writelane_b32 v252, s63, 20
	s_cselect_b64 s[62:63], -1, 0
	v_writelane_b32 v252, s62, 21
	s_cmp_eq_u32 s10, 9
	s_nop 0
	v_writelane_b32 v252, s63, 22
	s_cselect_b64 s[62:63], -1, 0
	v_writelane_b32 v252, s62, 23
	s_cmp_eq_u32 s10, 8
	s_nop 0
	v_writelane_b32 v252, s63, 24
	s_cselect_b64 s[62:63], -1, 0
	v_writelane_b32 v252, s62, 25
	s_cmp_eq_u32 s10, 7
	s_nop 0
	v_writelane_b32 v252, s63, 26
	s_cselect_b64 s[62:63], -1, 0
	v_writelane_b32 v252, s62, 27
	s_cmp_eq_u32 s10, 6
	s_nop 0
	v_writelane_b32 v252, s63, 28
	s_cselect_b64 s[62:63], -1, 0
	v_writelane_b32 v252, s62, 29
	s_cmp_eq_u32 s10, 5
	s_nop 0
	v_writelane_b32 v252, s63, 30
	s_cselect_b64 s[62:63], -1, 0
	v_writelane_b32 v252, s62, 31
	s_cmp_eq_u32 s10, 4
	s_nop 0
	v_writelane_b32 v252, s63, 32
	s_cselect_b64 s[62:63], -1, 0
	v_writelane_b32 v252, s62, 33
	s_cmp_eq_u32 s10, 3
	s_nop 0
	v_writelane_b32 v252, s63, 34
	s_cselect_b64 s[62:63], -1, 0
	v_writelane_b32 v252, s62, 35
	s_cmp_eq_u32 s10, 2
	s_nop 0
	v_writelane_b32 v252, s63, 36
	s_cselect_b64 s[62:63], -1, 0
	v_writelane_b32 v252, s62, 37
	s_cmp_eq_u32 s10, 1
	s_nop 0
	v_writelane_b32 v252, s63, 38
	s_cselect_b64 s[62:63], -1, 0
	v_writelane_b32 v252, s62, 39
	s_cmp_eq_u32 s10, 0
	s_nop 0
	v_writelane_b32 v252, s63, 40
	s_cselect_b64 s[62:63], -1, 0
	s_lshl_b32 s10, s10, 8
	s_add_u32 s2, s2, s10
	v_writelane_b32 v252, s62, 41
	s_addc_u32 s3, s3, 0
	s_nop 0
	v_writelane_b32 v252, s63, 42
	s_add_u32 s62, s2, 0x1400
	s_addc_u32 s63, s3, 0
	v_writelane_b32 v252, s62, 43
	s_add_u32 s2, s2, 0x2400
	s_addc_u32 s3, s3, 0
	v_writelane_b32 v252, s63, 44
	v_writelane_b32 v252, s2, 45
	s_nop 1
	v_writelane_b32 v252, s3, 46
	s_add_u32 s2, s24, 0x5016400
	s_addc_u32 s3, s25, 0
	v_writelane_b32 v252, s2, 47
	s_nop 1
	v_writelane_b32 v252, s3, 48
	s_add_u32 s2, s24, 0x5016500
	s_addc_u32 s3, s25, 0
	v_writelane_b32 v252, s2, 49
	s_nop 1
	v_writelane_b32 v252, s3, 50
	s_and_b64 s[2:3], s[4:5], exec
	s_cselect_b32 s2, s8, s15
	v_writelane_b32 v252, s2, 51
	s_cselect_b32 s6, s6, 32
	v_writelane_b32 v252, s6, 52
	s_cselect_b32 s6, 0x58, 4
	s_cselect_b32 s2, s57, s17
	v_writelane_b32 v252, s6, 53
	s_cselect_b32 s6, 0, 2
	s_cselect_b32 s3, s30, s18
	s_cselect_b32 s5, s29, s16
	s_cselect_b32 s4, s19, s14
	s_cselect_b32 s15, s45, s43
	s_cselect_b32 s14, s44, s41
	s_cselect_b32 s17, s42, s38
	s_cselect_b32 s16, s40, s37
	v_writelane_b32 v252, s6, 54
	s_cselect_b32 s6, 32, 4
	s_add_u32 s18, s2, 0x160000
	v_writelane_b32 v252, s6, 55
	s_addc_u32 s19, s3, 0
	v_writelane_b32 v252, s18, 56
	s_mov_b32 s37, 0
	s_mov_b32 s75, s37
	v_writelane_b32 v252, s19, 57
	s_add_u32 s18, s4, 0x2c0000
	v_writelane_b32 v252, s4, 58
	s_addc_u32 s19, s5, 0
	s_mov_b32 s61, s37
	v_writelane_b32 v252, s5, 59
	v_writelane_b32 v252, s18, 60
	s_add_u32 s4, s2, 0x160080
	s_mov_b32 s30, 0x3f07dc22
	v_writelane_b32 v252, s19, 61
	v_writelane_b32 v252, s2, 62
	s_addc_u32 s5, s3, 0
	v_writelane_b32 v253, s4, 0
	v_writelane_b32 v252, s3, 63
	s_add_u32 s2, s14, 0x80000
	v_writelane_b32 v253, s5, 1
	s_addc_u32 s3, s15, 0
	v_writelane_b32 v253, s2, 2
	s_nop 1
	v_writelane_b32 v253, s3, 3
	s_add_u32 s2, s16, 0x80000
	v_writelane_b32 v253, s16, 4
	s_addc_u32 s3, s17, 0
	s_nop 0
	v_writelane_b32 v253, s17, 5
	v_writelane_b32 v253, s2, 6
	s_nop 1
	v_writelane_b32 v253, s3, 7
	s_add_u32 s2, s14, 0x80080
	v_writelane_b32 v253, s14, 8
	s_addc_u32 s3, s15, 0
	s_nop 0
	v_writelane_b32 v253, s15, 9
	v_writelane_b32 v253, s2, 10
	s_nop 1
	v_writelane_b32 v253, s3, 11
	s_sub_i32 s2, 0, s11
	v_readfirstlane_b32 s3, v1
	s_mul_i32 s2, s2, s3
	s_mul_hi_u32 s2, s3, s2
	s_add_i32 s3, s3, s2
	s_abs_i32 s2, s13
	s_mul_hi_u32 s3, s2, s3
	s_mul_i32 s4, s3, s11
	s_sub_i32 s2, s2, s4
	s_ashr_i32 s4, s13, 31
	s_add_i32 s5, s3, 1
	s_sub_i32 s6, s2, s11
	s_cmp_ge_u32 s2, s11
	s_cselect_b32 s3, s5, s3
	s_cselect_b32 s2, s6, s2
	s_add_i32 s5, s3, 1
	s_cmp_ge_u32 s2, s11
	s_cselect_b32 s2, s5, s3
	s_xor_b32 s2, s2, s4
	s_sub_i32 s4, s2, s4
	s_mul_i32 s11, s11, s4
	s_sub_i32 s10, s12, s11
	s_mov_b32 s2, s10
	s_ashr_i32 s11, s10, 31
	v_writelane_b32 v253, s2, 12
	v_cvt_f32_ubyte0_e32 v1, s7
	v_rcp_iflag_f32_e32 v1, v1
	v_writelane_b32 v253, s3, 13
	s_lshl_b64 s[2:3], s[10:11], 20
	s_add_u32 s10, s48, s2
	s_mov_b32 s2, s4
	s_addc_u32 s11, s49, s3
	s_ashr_i32 s5, s4, 31
	v_writelane_b32 v253, s2, 14
	v_mul_f32_e32 v1, 0x4f7ffffe, v1
	v_cvt_u32_f32_e32 v1, v1
	v_writelane_b32 v253, s3, 15
	s_lshl_b64 s[2:3], s[4:5], 20
	s_add_u32 s2, s50, s2
	v_writelane_b32 v253, s50, 16
	s_addc_u32 s3, s51, s3
	s_add_u32 s4, s2, 0x80000
	v_writelane_b32 v253, s51, 17
	s_addc_u32 s5, s3, 0
	v_writelane_b32 v253, s4, 18
	s_nop 1
	v_writelane_b32 v253, s5, 19
	s_add_u32 s4, s10, 0x80000
	v_writelane_b32 v253, s10, 20
	s_addc_u32 s5, s11, 0
	s_nop 0
	v_writelane_b32 v253, s11, 21
	v_writelane_b32 v253, s4, 22
	s_nop 1
	v_writelane_b32 v253, s5, 23
	s_add_u32 s4, s2, 0x80080
	v_writelane_b32 v253, s2, 24
	s_addc_u32 s5, s3, 0
	s_nop 0
	v_writelane_b32 v253, s3, 25
	s_sub_i32 s2, 0, s7
	v_readfirstlane_b32 s3, v1
	s_mul_i32 s2, s2, s3
	s_mul_hi_u32 s2, s3, s2
	s_add_i32 s3, s3, s2
	s_abs_i32 s2, s31
	v_writelane_b32 v253, s4, 26
	s_mul_hi_u32 s3, s2, s3
	v_cvt_f32_ubyte0_e32 v1, s33
	v_writelane_b32 v253, s5, 27
	s_mul_i32 s4, s3, s7
	s_sub_i32 s2, s2, s4
	s_ashr_i32 s4, s31, 31
	s_add_i32 s5, s3, 1
	s_sub_i32 s6, s2, s7
	s_cmp_ge_u32 s2, s7
	s_cselect_b32 s3, s5, s3
	s_cselect_b32 s2, s6, s2
	s_add_i32 s5, s3, 1
	s_cmp_ge_u32 s2, s7
	s_cselect_b32 s2, s5, s3
	s_xor_b32 s2, s2, s4
	s_sub_i32 s2, s2, s4
	s_mul_i32 s7, s7, s2
	v_rcp_iflag_f32_e32 v1, v1
	s_sub_i32 s4, s9, s7
	s_add_i32 s3, s2, 4
	s_cmp_lt_i32 s2, 8
	s_cselect_b32 s6, s2, s3
	s_mov_b32 s2, s4
	s_ashr_i32 s5, s4, 31
	v_writelane_b32 v253, s2, 28
	v_mul_f32_e32 v1, 0x4f7ffffe, v1
	v_cvt_u32_f32_e32 v1, v1
	v_writelane_b32 v253, s3, 29
	s_lshl_b64 s[2:3], s[4:5], 20
	s_add_u32 s2, s48, s2
	s_addc_u32 s3, s49, s3
	v_writelane_b32 v253, s2, 30
	s_ashr_i32 s7, s6, 31
	s_mov_b32 s31, 0x3e6d3388
	v_writelane_b32 v253, s3, 31
	s_sub_i32 s2, 0, s33
	v_readfirstlane_b32 s3, v1
	s_mul_i32 s2, s2, s3
	s_mul_hi_u32 s2, s3, s2
	s_add_i32 s3, s3, s2
	s_abs_i32 s2, s39
	s_mul_hi_u32 s3, s2, s3
	s_mul_i32 s4, s3, s33
	s_sub_i32 s2, s2, s4
	v_writelane_b32 v253, s6, 32
	s_ashr_i32 s4, s39, 31
	s_add_i32 s5, s3, 1
	v_writelane_b32 v253, s7, 33
	s_sub_i32 s6, s2, s33
	s_cmp_ge_u32 s2, s33
	s_cselect_b32 s3, s5, s3
	s_cselect_b32 s2, s6, s2
	s_add_i32 s5, s3, 1
	s_cmp_ge_u32 s2, s33
	s_cselect_b32 s2, s5, s3
	s_xor_b32 s2, s2, s4
	s_sub_i32 s2, s2, s4
	s_mul_i32 s33, s33, s2
	s_sub_i32 s4, s36, s33
	s_add_i32 s3, s2, 4
	s_cmp_lt_i32 s2, 8
	s_cselect_b32 s6, s2, s3
	s_mov_b32 s2, s4
	s_ashr_i32 s5, s4, 31
	v_writelane_b32 v253, s2, 34
	v_lshrrev_b32_e32 v1, 20, v0
	v_lshrrev_b32_e32 v0, 10, v0
	v_writelane_b32 v253, s3, 35
	s_lshl_b64 s[2:3], s[4:5], 20
	s_add_u32 s2, s48, s2
	v_writelane_b32 v253, s48, 36
	s_addc_u32 s3, s49, s3
	s_ashr_i32 s7, s6, 31
	v_writelane_b32 v253, s49, 37
	v_writelane_b32 v253, s2, 38
	v_or_b32_e32 v0, v0, v1
	v_mov_b32_e32 v1, 0
	v_writelane_b32 v253, s3, 39
	v_writelane_b32 v253, s6, 40
	s_lshl_b32 s2, s68, 11
	s_mov_b32 s33, 0x3f317217
	v_writelane_b32 v253, s7, 41
	v_writelane_b32 v253, s2, 42
	s_lshl_b32 s2, s52, 11
	v_writelane_b32 v253, s2, 43
	s_add_u32 s2, s24, 0x8a40400
	s_addc_u32 s3, s25, 0
	v_writelane_b32 v253, s2, 44
	s_load_dwordx16 s[4:19], s[0:1], 0x0
	s_nop 0
	v_writelane_b32 v253, s3, 45
	s_add_u32 s2, s24, 0x4f08000
	v_writelane_b32 v253, s2, 46
	s_addc_u32 s2, s25, 0
	v_writelane_b32 v253, s2, 47
	s_lshl_b32 s2, s68, 7
	s_ashr_i32 s29, s28, 31
	v_writelane_b32 v253, s2, 48
	s_lshl_b32 s2, s52, 7
	v_writelane_b32 v253, s2, 49
	s_lshl_b64 s[2:3], s[28:29], 4
	s_ashr_i32 s57, s56, 31
	v_writelane_b32 v253, s2, 50
	s_nop 1
	v_writelane_b32 v253, s3, 51
	s_lshl_b64 s[2:3], s[56:57], 12
	v_writelane_b32 v253, s2, 52
	s_nop 1
	v_writelane_b32 v253, s3, 53
	s_lshl_b64 s[2:3], s[56:57], 6
	v_writelane_b32 v253, s2, 54
	s_nop 1
	v_writelane_b32 v253, s3, 55
	s_lshl_b64 s[2:3], s[56:57], 11
	v_writelane_b32 v253, s2, 56
	s_nop 1
	v_writelane_b32 v253, s3, 57
	s_waitcnt lgkmcnt(0)
	s_add_u32 s2, s12, 16
	v_writelane_b32 v253, s4, 58
	s_addc_u32 s3, s13, 0
	s_nop 0
	v_writelane_b32 v254, s10, 0
	v_writelane_b32 v254, s11, 1
	v_writelane_b32 v254, s12, 2
	v_writelane_b32 v254, s13, 3
	v_writelane_b32 v254, s14, 4
	v_writelane_b32 v254, s15, 5
	v_writelane_b32 v254, s16, 6
	v_writelane_b32 v254, s17, 7
	v_writelane_b32 v254, s18, 8
	v_writelane_b32 v254, s19, 9
	v_writelane_b32 v254, s2, 10
	s_mov_b64 s[18:19], s[28:29]
	v_writelane_b32 v253, s5, 59
	v_writelane_b32 v254, s3, 11
	s_lshl_b64 s[2:3], s[28:29], 5
	v_writelane_b32 v254, s2, 12
	v_writelane_b32 v253, s6, 60
	v_writelane_b32 v253, s7, 61
	v_writelane_b32 v254, s3, 13
	s_add_u32 s2, s24, 0x162f7000
	s_addc_u32 s3, s25, 0
	v_writelane_b32 v254, s2, 14
	s_mov_b64 s[6:7], vcc
	v_writelane_b32 v253, s8, 62
	v_writelane_b32 v254, s3, 15
	s_lshl_b32 s2, s68, 6
	v_writelane_b32 v254, s2, 16
	s_lshl_b32 s2, s52, 6
	s_mul_i32 s3, s68, 0xc000
	v_writelane_b32 v254, s2, 17
	s_mul_hi_i32 s2, s68, 0xc000
	s_add_u32 s12, s24, s3
	s_addc_u32 s13, s25, s2
	v_writelane_b32 v254, s12, 18
	s_movk_i32 s2, 0x3ff
	v_and_or_b32 v0, v0, s2, v159
	v_writelane_b32 v254, s13, 19
	v_writelane_b32 v254, s74, 20
	s_add_i32 s2, s68, 12
	v_cmp_eq_u32_e64 s[12:13], 0, v0
	v_writelane_b32 v254, s75, 21
	v_writelane_b32 v254, s60, 22
	v_writelane_b32 v253, s9, 63
	s_mov_b64 s[8:9], s[70:71]
	v_writelane_b32 v254, s61, 23
	v_writelane_b32 v254, s2, 24
	s_add_i32 s2, s68, 24
	v_writelane_b32 v254, s2, 25
	s_add_i32 s2, s68, 36
	v_writelane_b32 v254, s2, 26
	s_add_i32 s2, s68, 48
	v_writelane_b32 v254, s2, 27
	s_add_i32 s2, s68, 60
	v_writelane_b32 v254, s2, 28
	s_add_i32 s2, s68, 0x48
	v_writelane_b32 v254, s2, 29
	s_add_i32 s2, s68, 0x54
	v_writelane_b32 v254, s2, 30
	s_lshl_b32 s2, s68, 8
	s_add_i32 s3, s2, 0xfff39c00
	v_writelane_b32 v254, s3, 31
	s_lshl_b32 s3, s52, 8
	v_writelane_b32 v254, s3, 32
	v_writelane_b32 v254, s2, 33
	s_add_i32 s2, s2, 0xfff3a000
	v_writelane_b32 v254, s2, 34
	s_add_i32 s2, s47, 0xb300
	v_writelane_b32 v254, s2, 35
	v_writelane_b32 v254, s47, 36
	s_add_i32 s2, s47, 0xe700
	v_writelane_b32 v254, s2, 37
	s_add_i32 s2, 0, 0x15020
	v_writelane_b32 v254, s2, 38
	s_add_i32 s2, 0, 0xffffc0c0
	v_writelane_b32 v254, s2, 39
	s_add_i32 s2, 0, 0x1ff80
	v_writelane_b32 v254, s2, 40
	s_add_i32 s2, 0, 0x20700
	s_load_dwordx16 s[40:55], s[0:1], 0xc0
	v_writelane_b32 v254, s2, 41
	s_add_i32 s2, 0, 0x20704
	v_writelane_b32 v254, s2, 42
	v_writelane_b32 v254, s12, 43
	s_mov_b64 s[10:11], s[72:73]
	s_mov_b32 s5, 0x800000
	v_writelane_b32 v254, s13, 44
	s_waitcnt lgkmcnt(0)
	v_writelane_b32 v254, s40, 45
	s_mov_b32 s16, 0x21000
	s_movk_i32 s29, 0xff80
	v_writelane_b32 v254, s41, 46
	v_writelane_b32 v254, s42, 47
	v_writelane_b32 v254, s43, 48
	v_writelane_b32 v254, s44, 49
	v_writelane_b32 v254, s45, 50
	v_writelane_b32 v254, s46, 51
	v_writelane_b32 v254, s47, 52
	v_writelane_b32 v254, s48, 53
	v_writelane_b32 v254, s49, 54
	v_writelane_b32 v254, s50, 55
	v_writelane_b32 v254, s51, 56
	v_writelane_b32 v254, s52, 57
	v_writelane_b32 v254, s53, 58
	v_writelane_b32 v254, s54, 59
	v_writelane_b32 v254, s55, 60
	s_load_dwordx16 s[40:55], s[0:1], 0x40
	s_mov_b32 s0, s68
	s_mov_b32 s15, 0xf149f2ca
	s_mov_b32 s3, 0xbfb8aa3b
	s_mov_b32 s14, 0x7f800000
	s_waitcnt lgkmcnt(0)
	v_writelane_b32 v254, s40, 61
	s_mov_b32 s4, 0x3f35f0e3
	s_mov_b32 s2, 0xbe11a98e
	v_writelane_b32 v255, s43, 0
	v_writelane_b32 v255, s44, 1
	v_writelane_b32 v255, s45, 2
	v_writelane_b32 v255, s46, 3
	v_writelane_b32 v255, s47, 4
	v_writelane_b32 v255, s48, 5
	v_writelane_b32 v255, s49, 6
	v_writelane_b32 v255, s50, 7
	v_writelane_b32 v255, s51, 8
	v_writelane_b32 v255, s52, 9
	v_writelane_b32 v255, s53, 10
	v_writelane_b32 v255, s54, 11
	v_writelane_b32 v255, s55, 12
	v_writelane_b32 v255, s0, 13
	v_writelane_b32 v254, s41, 62
	s_mov_b32 s28, 0x3fb8aa3b
	v_writelane_b32 v255, s1, 14
	s_mov_b32 s0, s88
	v_writelane_b32 v255, s0, 15
	v_writelane_b32 v254, s42, 63
	s_nop 0
	v_writelane_b32 v255, s1, 16
	v_writelane_b32 v255, s90, 17
	s_mov_b32 s0, s18
	s_nop 0
	v_writelane_b32 v255, s91, 18
	v_writelane_b32 v255, s96, 19
	s_nop 1
	v_writelane_b32 v255, s97, 20
	v_writelane_b32 v255, s0, 21
	s_nop 1
	v_writelane_b32 v255, s1, 22
	v_writelane_b32 v255, s6, 23
	s_mov_b32 s0, s56
	s_nop 0
	v_writelane_b32 v255, s7, 24
	v_writelane_b32 v255, s8, 25
	s_nop 1
	v_writelane_b32 v255, s9, 26
	v_writelane_b32 v255, s10, 27
	s_nop 1
	v_writelane_b32 v255, s11, 28
	v_writelane_b32 v255, s0, 29
	s_nop 1
	v_writelane_b32 v255, s1, 30
	v_writelane_b32 v255, s64, 31
	s_nop 1
	v_writelane_b32 v255, s65, 32
	v_writelane_b32 v255, s66, 33
	s_nop 1
	v_writelane_b32 v255, s67, 34
	v_writelane_b32 v255, s58, 35
	s_nop 1
	v_writelane_b32 v255, s59, 36
	v_writelane_b32 v255, s78, 37
	s_nop 1
	v_writelane_b32 v255, s79, 38
	s_branch .LBB0_10

.LBB0_10:
	s_waitcnt lgkmcnt(0)
	s_mov_b32 s0, 0x87643210
	s_mov_b32 s1, 0xda9
	s_lshl_b32 s17, s26, 2
	s_lshr_b64 s[0:1], s[0:1], s17
	s_and_b32 s17, s0, 15
	v_mov_b32_e32 v166, v159
	s_cmp_lt_i32 s17, 6
	s_mov_b64 s[0:1], -1
	s_cbranch_scc1 .LBB0_430
	s_cmp_lt_i32 s17, 9
	s_cbranch_scc1 .LBB0_220
	s_cmp_lt_i32 s17, 10
	s_cbranch_scc1 .LBB0_178
	s_cmp_gt_i32 s17, 12
	s_cbranch_scc0 .LBB0_18
	v_readlane_b32 s0, v250, 15
	s_waitcnt vmcnt(0)
	s_nop 0
	v_add_u32_e32 v12, s0, v166
	s_mov_b32 s0, 0x10000
	v_cmp_gt_i32_e32 vcc, s0, v12
	s_and_saveexec_b64 s[0:1], vcc
	v_readlane_b32 s36, v253, 43
	s_mov_b32 s40, 0xd00000
	s_mov_b32 s41, 0xffff
	s_cbranch_execz .LBB0_17
	v_readlane_b32 s12, v253, 42
	s_mov_b64 s[38:39], 0
	s_nop 0
	v_lshl_add_u32 v13, v166, 2, s12

.Lsc_chunk:
	s_waitcnt lgkmcnt(5)
	v_pk_mul_f32 v[156:157], v[54:55], v[80:81]
	v_pk_fma_f32 v[156:157], v[56:57], v[82:83], v[156:157]
	v_add_f32_e32 v2, v156, v157
	ds_read_b128 v[120:123], v32 offset:3328
	ds_read_b128 v[116:119], v32 offset:3072
	v_add_f32_dpp v2, v2, v2 row_ror:8 row_mask:0xf bank_mask:0xf bound_ctrl:1
	ds_read2_b32 v[150:151], v33 offset0:32 offset1:48
	v_pk_mul_f32 v[4:5], v[76:77], v[148:149] op_sel_hi:[1,0]
	v_add_f32_dpp v2, v2, v2 row_ror:4 row_mask:0xf bank_mask:0xf bound_ctrl:1
	v_pk_mul_f32 v[6:7], v[78:79], v[148:149] op_sel_hi:[1,0]
	v_pk_fma_f32 v[4:5], v[54:55], v[68:69], v[4:5]
	v_add_f32_dpp v2, v2, v2 row_ror:2 row_mask:0xf bank_mask:0xf bound_ctrl:1
	v_pk_fma_f32 v[6:7], v[56:57], v[70:71], v[6:7]
	ds_read_b128 v[108:111], v32 offset:2560
	v_add_f32_dpp v2, v2, v2 row_ror:1 row_mask:0xf bank_mask:0xf bound_ctrl:1
	v_pk_fma_f32 v[54:55], v[84:85], v[2:3], v[4:5] op_sel_hi:[1,0,1] neg_lo:[1,0,0] neg_hi:[1,0,0]
	v_pk_fma_f32 v[56:57], v[86:87], v[2:3], v[6:7] op_sel_hi:[1,0,1] neg_lo:[1,0,0] neg_hi:[1,0,0]
	ds_read_b128 v[124:127], v32 offset:3584
	ds_read_b128 v[112:115], v32 offset:2816
	s_waitcnt lgkmcnt(6)
	v_pk_mul_f32 v[156:157], v[54:55], v[100:101]
	v_pk_fma_f32 v[156:157], v[56:57], v[102:103], v[156:157]
	v_add_f32_e32 v2, v156, v157
	v_pk_mul_f32 v[8:9], v[54:55], v[72:73]
	v_pk_fma_f32 v[8:9], v[56:57], v[74:75], v[8:9]
	v_add_f32_dpp v2, v2, v2 row_ror:8 row_mask:0xf bank_mask:0xf bound_ctrl:1
	v_add_f32_e32 v66, v8, v9
	v_pk_mul_f32 v[4:5], v[96:97], v[148:149] op_sel:[0,1] op_sel_hi:[1,1]
	v_add_f32_dpp v2, v2, v2 row_ror:4 row_mask:0xf bank_mask:0xf bound_ctrl:1
	v_pk_mul_f32 v[6:7], v[98:99], v[148:149] op_sel:[0,1] op_sel_hi:[1,1]
	v_pk_fma_f32 v[4:5], v[54:55], v[88:89], v[4:5]
	v_add_f32_dpp v2, v2, v2 row_ror:2 row_mask:0xf bank_mask:0xf bound_ctrl:1
	v_pk_fma_f32 v[6:7], v[56:57], v[90:91], v[6:7]
	ds_read_b128 v[140:143], v32 offset:4608
	v_add_f32_dpp v2, v2, v2 row_ror:1 row_mask:0xf bank_mask:0xf bound_ctrl:1
	v_pk_fma_f32 v[54:55], v[104:105], v[2:3], v[4:5] op_sel_hi:[1,0,1] neg_lo:[1,0,0] neg_hi:[1,0,0]
	v_pk_fma_f32 v[56:57], v[106:107], v[2:3], v[6:7] op_sel_hi:[1,0,1] neg_lo:[1,0,0] neg_hi:[1,0,0]
	ds_read_b128 v[136:139], v32 offset:4352
	ds_read_b128 v[128:131], v32 offset:3840
	ds_read_b128 v[144:147], v32 offset:4864
	ds_read_b128 v[132:135], v32 offset:4096
	s_waitcnt lgkmcnt(5)
	v_pk_mul_f32 v[156:157], v[54:55], v[120:121]
	v_pk_fma_f32 v[156:157], v[56:57], v[122:123], v[156:157]
	v_add_f32_e32 v2, v156, v157
	v_pk_mul_f32 v[8:9], v[54:55], v[92:93]
	v_pk_fma_f32 v[8:9], v[56:57], v[94:95], v[8:9]
	v_add_f32_dpp v2, v2, v2 row_ror:8 row_mask:0xf bank_mask:0xf bound_ctrl:1
	v_add_f32_e32 v10, v8, v9
	v_pk_mul_f32 v[4:5], v[116:117], v[150:151] op_sel_hi:[1,0]
	v_add_f32_dpp v2, v2, v2 row_ror:4 row_mask:0xf bank_mask:0xf bound_ctrl:1
	v_pk_mul_f32 v[6:7], v[118:119], v[150:151] op_sel_hi:[1,0]
	v_pk_fma_f32 v[4:5], v[54:55], v[108:109], v[4:5]
	v_add_f32_dpp v2, v2, v2 row_ror:2 row_mask:0xf bank_mask:0xf bound_ctrl:1
	v_pk_fma_f32 v[6:7], v[56:57], v[110:111], v[6:7]
	ds_read_b128 v[80:83], v32 offset:5888
	v_add_f32_dpp v2, v2, v2 row_ror:1 row_mask:0xf bank_mask:0xf bound_ctrl:1
	v_pk_fma_f32 v[54:55], v[124:125], v[2:3], v[4:5] op_sel_hi:[1,0,1] neg_lo:[1,0,0] neg_hi:[1,0,0]
	v_pk_fma_f32 v[56:57], v[126:127], v[2:3], v[6:7] op_sel_hi:[1,0,1] neg_lo:[1,0,0] neg_hi:[1,0,0]
	ds_read_b128 v[76:79], v32 offset:5632
	ds_read2_b32 v[152:153], v33 offset0:64 offset1:80
	ds_read_b128 v[68:71], v32 offset:5120
	ds_read_b128 v[84:87], v32 offset:6144
	ds_read_b128 v[72:75], v32 offset:5376
	s_waitcnt lgkmcnt(6)
	v_pk_mul_f32 v[156:157], v[54:55], v[140:141]
	v_pk_fma_f32 v[156:157], v[56:57], v[142:143], v[156:157]
	v_add_f32_e32 v2, v156, v157
	v_pk_mul_f32 v[8:9], v[54:55], v[112:113]
	v_pk_fma_f32 v[8:9], v[56:57], v[114:115], v[8:9]
	v_add_f32_dpp v2, v2, v2 row_ror:8 row_mask:0xf bank_mask:0xf bound_ctrl:1
	v_add_f32_e32 v11, v8, v9
	v_pk_mul_f32 v[4:5], v[136:137], v[150:151] op_sel:[0,1] op_sel_hi:[1,1]
	v_add_f32_dpp v2, v2, v2 row_ror:4 row_mask:0xf bank_mask:0xf bound_ctrl:1
	v_pk_mul_f32 v[6:7], v[138:139], v[150:151] op_sel:[0,1] op_sel_hi:[1,1]
	v_pk_fma_f32 v[4:5], v[54:55], v[128:129], v[4:5]
	v_add_f32_dpp v2, v2, v2 row_ror:2 row_mask:0xf bank_mask:0xf bound_ctrl:1
	v_pk_fma_f32 v[6:7], v[56:57], v[130:131], v[6:7]
	ds_read_b128 v[100:103], v32 offset:7168
	v_add_f32_dpp v2, v2, v2 row_ror:1 row_mask:0xf bank_mask:0xf bound_ctrl:1
	v_pk_fma_f32 v[54:55], v[144:145], v[2:3], v[4:5] op_sel_hi:[1,0,1] neg_lo:[1,0,0] neg_hi:[1,0,0]
	v_pk_fma_f32 v[56:57], v[146:147], v[2:3], v[6:7] op_sel_hi:[1,0,1] neg_lo:[1,0,0] neg_hi:[1,0,0]
	ds_read_b128 v[96:99], v32 offset:6912
	ds_read_b128 v[88:91], v32 offset:6400
	ds_read_b128 v[104:107], v32 offset:7424
	ds_read_b128 v[92:95], v32 offset:6656
	s_waitcnt lgkmcnt(5)
	v_pk_mul_f32 v[156:157], v[54:55], v[80:81]
	v_pk_fma_f32 v[156:157], v[56:57], v[82:83], v[156:157]
	v_add_f32_e32 v2, v156, v157
	v_pk_mul_f32 v[8:9], v[54:55], v[132:133]
	v_pk_fma_f32 v[8:9], v[56:57], v[134:135], v[8:9]
	v_add_f32_dpp v2, v2, v2 row_ror:8 row_mask:0xf bank_mask:0xf bound_ctrl:1
	v_add_f32_e32 v12, v8, v9
	v_pk_mul_f32 v[4:5], v[76:77], v[152:153] op_sel_hi:[1,0]
	v_add_f32_dpp v2, v2, v2 row_ror:4 row_mask:0xf bank_mask:0xf bound_ctrl:1
	v_pk_mul_f32 v[6:7], v[78:79], v[152:153] op_sel_hi:[1,0]
	v_pk_fma_f32 v[4:5], v[54:55], v[68:69], v[4:5]
	v_add_f32_dpp v2, v2, v2 row_ror:2 row_mask:0xf bank_mask:0xf bound_ctrl:1
	v_pk_fma_f32 v[6:7], v[56:57], v[70:71], v[6:7]
	ds_read_b128 v[120:123], v32 offset:8448
	v_add_f32_dpp v2, v2, v2 row_ror:1 row_mask:0xf bank_mask:0xf bound_ctrl:1
	v_pk_fma_f32 v[54:55], v[84:85], v[2:3], v[4:5] op_sel_hi:[1,0,1] neg_lo:[1,0,0] neg_hi:[1,0,0]
	v_pk_fma_f32 v[56:57], v[86:87], v[2:3], v[6:7] op_sel_hi:[1,0,1] neg_lo:[1,0,0] neg_hi:[1,0,0]
	ds_read_b128 v[116:119], v32 offset:8192
	ds_read2_b32 v[154:155], v33 offset0:96 offset1:112
	ds_read_b128 v[108:111], v32 offset:7680
	ds_read_b128 v[124:127], v32 offset:8704
	ds_read_b128 v[112:115], v32 offset:7936
	s_waitcnt lgkmcnt(6)
	v_pk_mul_f32 v[156:157], v[54:55], v[100:101]
	v_pk_fma_f32 v[156:157], v[56:57], v[102:103], v[156:157]
	v_add_f32_e32 v2, v156, v157
	v_pk_mul_f32 v[8:9], v[54:55], v[72:73]
	v_pk_fma_f32 v[8:9], v[56:57], v[74:75], v[8:9]
	v_add_f32_dpp v2, v2, v2 row_ror:8 row_mask:0xf bank_mask:0xf bound_ctrl:1
	v_add_f32_e32 v13, v8, v9
	v_pk_mul_f32 v[4:5], v[96:97], v[152:153] op_sel:[0,1] op_sel_hi:[1,1]
	v_add_f32_dpp v2, v2, v2 row_ror:4 row_mask:0xf bank_mask:0xf bound_ctrl:1
	v_pk_mul_f32 v[6:7], v[98:99], v[152:153] op_sel:[0,1] op_sel_hi:[1,1]
	v_pk_fma_f32 v[4:5], v[54:55], v[88:89], v[4:5]
	v_add_f32_dpp v2, v2, v2 row_ror:2 row_mask:0xf bank_mask:0xf bound_ctrl:1
	v_pk_fma_f32 v[6:7], v[56:57], v[90:91], v[6:7]
	ds_read_b128 v[140:143], v32 offset:9728
	v_add_f32_dpp v2, v2, v2 row_ror:1 row_mask:0xf bank_mask:0xf bound_ctrl:1
	v_pk_fma_f32 v[54:55], v[104:105], v[2:3], v[4:5] op_sel_hi:[1,0,1] neg_lo:[1,0,0] neg_hi:[1,0,0]
	v_pk_fma_f32 v[56:57], v[106:107], v[2:3], v[6:7] op_sel_hi:[1,0,1] neg_lo:[1,0,0] neg_hi:[1,0,0]
	ds_read_b128 v[136:139], v32 offset:9472
	ds_read_b128 v[128:131], v32 offset:8960
	ds_read_b128 v[144:147], v32 offset:9984
	ds_read_b128 v[132:135], v32 offset:9216
	s_waitcnt lgkmcnt(5)
	v_pk_mul_f32 v[156:157], v[54:55], v[120:121]
	v_pk_fma_f32 v[156:157], v[56:57], v[122:123], v[156:157]
	v_add_f32_e32 v2, v156, v157
	v_pk_mul_f32 v[8:9], v[54:55], v[92:93]
	v_pk_fma_f32 v[8:9], v[56:57], v[94:95], v[8:9]
	v_add_f32_dpp v2, v2, v2 row_ror:8 row_mask:0xf bank_mask:0xf bound_ctrl:1
	v_add_f32_e32 v14, v8, v9
	v_pk_mul_f32 v[4:5], v[116:117], v[154:155] op_sel_hi:[1,0]
	v_add_f32_dpp v2, v2, v2 row_ror:4 row_mask:0xf bank_mask:0xf bound_ctrl:1
	v_pk_mul_f32 v[6:7], v[118:119], v[154:155] op_sel_hi:[1,0]
	v_pk_fma_f32 v[4:5], v[54:55], v[108:109], v[4:5]
	v_add_f32_dpp v2, v2, v2 row_ror:2 row_mask:0xf bank_mask:0xf bound_ctrl:1
	v_pk_fma_f32 v[6:7], v[56:57], v[110:111], v[6:7]
	ds_read_b128 v[80:83], v32 offset:11008
	v_add_f32_dpp v2, v2, v2 row_ror:1 row_mask:0xf bank_mask:0xf bound_ctrl:1
	v_pk_fma_f32 v[54:55], v[124:125], v[2:3], v[4:5] op_sel_hi:[1,0,1] neg_lo:[1,0,0] neg_hi:[1,0,0]
	v_pk_fma_f32 v[56:57], v[126:127], v[2:3], v[6:7] op_sel_hi:[1,0,1] neg_lo:[1,0,0] neg_hi:[1,0,0]
	ds_read_b128 v[76:79], v32 offset:10752
	ds_read2_b32 v[148:149], v33 offset0:128 offset1:144
	ds_read_b128 v[68:71], v32 offset:10240
	ds_read_b128 v[84:87], v32 offset:11264
	ds_read_b128 v[72:75], v32 offset:10496
	s_waitcnt lgkmcnt(6)
	v_pk_mul_f32 v[156:157], v[54:55], v[140:141]
	v_pk_fma_f32 v[156:157], v[56:57], v[142:143], v[156:157]
	v_add_f32_e32 v2, v156, v157
	v_pk_mul_f32 v[8:9], v[54:55], v[112:113]
	v_pk_fma_f32 v[8:9], v[56:57], v[114:115], v[8:9]
	v_add_f32_dpp v2, v2, v2 row_ror:8 row_mask:0xf bank_mask:0xf bound_ctrl:1
	v_add_f32_e32 v15, v8, v9
	v_pk_mul_f32 v[4:5], v[136:137], v[154:155] op_sel:[0,1] op_sel_hi:[1,1]
	v_add_f32_dpp v2, v2, v2 row_ror:4 row_mask:0xf bank_mask:0xf bound_ctrl:1
	v_pk_mul_f32 v[6:7], v[138:139], v[154:155] op_sel:[0,1] op_sel_hi:[1,1]
	v_pk_fma_f32 v[4:5], v[54:55], v[128:129], v[4:5]
	v_add_f32_dpp v2, v2, v2 row_ror:2 row_mask:0xf bank_mask:0xf bound_ctrl:1
	v_pk_fma_f32 v[6:7], v[56:57], v[130:131], v[6:7]
	ds_read_b128 v[100:103], v32 offset:12288
	v_add_f32_dpp v2, v2, v2 row_ror:1 row_mask:0xf bank_mask:0xf bound_ctrl:1
	v_pk_fma_f32 v[54:55], v[144:145], v[2:3], v[4:5] op_sel_hi:[1,0,1] neg_lo:[1,0,0] neg_hi:[1,0,0]
	v_pk_fma_f32 v[56:57], v[146:147], v[2:3], v[6:7] op_sel_hi:[1,0,1] neg_lo:[1,0,0] neg_hi:[1,0,0]
	ds_read_b128 v[96:99], v32 offset:12032
	ds_read_b128 v[88:91], v32 offset:11520
	ds_read_b128 v[104:107], v32 offset:12544
	ds_read_b128 v[92:95], v32 offset:11776
	s_waitcnt lgkmcnt(5)
	v_pk_mul_f32 v[156:157], v[54:55], v[80:81]
	v_pk_fma_f32 v[156:157], v[56:57], v[82:83], v[156:157]
	v_add_f32_e32 v2, v156, v157
	v_pk_mul_f32 v[8:9], v[54:55], v[132:133]
	v_pk_fma_f32 v[8:9], v[56:57], v[134:135], v[8:9]
	v_add_f32_dpp v2, v2, v2 row_ror:8 row_mask:0xf bank_mask:0xf bound_ctrl:1
	v_add_f32_e32 v16, v8, v9
	v_pk_mul_f32 v[4:5], v[76:77], v[148:149] op_sel_hi:[1,0]
	v_add_f32_dpp v2, v2, v2 row_ror:4 row_mask:0xf bank_mask:0xf bound_ctrl:1
	v_pk_mul_f32 v[6:7], v[78:79], v[148:149] op_sel_hi:[1,0]
	v_pk_fma_f32 v[4:5], v[54:55], v[68:69], v[4:5]
	v_add_f32_dpp v2, v2, v2 row_ror:2 row_mask:0xf bank_mask:0xf bound_ctrl:1
	v_pk_fma_f32 v[6:7], v[56:57], v[70:71], v[6:7]
	ds_read_b128 v[120:123], v32 offset:13568
	v_add_f32_dpp v2, v2, v2 row_ror:1 row_mask:0xf bank_mask:0xf bound_ctrl:1
	v_pk_fma_f32 v[54:55], v[84:85], v[2:3], v[4:5] op_sel_hi:[1,0,1] neg_lo:[1,0,0] neg_hi:[1,0,0]
	v_pk_fma_f32 v[56:57], v[86:87], v[2:3], v[6:7] op_sel_hi:[1,0,1] neg_lo:[1,0,0] neg_hi:[1,0,0]
	ds_read_b128 v[116:119], v32 offset:13312
	ds_read2_b32 v[150:151], v33 offset0:160 offset1:176
	ds_read_b128 v[108:111], v32 offset:12800
	ds_read_b128 v[124:127], v32 offset:13824
	ds_read_b128 v[112:115], v32 offset:13056
	s_waitcnt lgkmcnt(6)
	v_pk_mul_f32 v[156:157], v[54:55], v[100:101]
	v_pk_fma_f32 v[156:157], v[56:57], v[102:103], v[156:157]
	v_add_f32_e32 v2, v156, v157
	v_pk_mul_f32 v[8:9], v[54:55], v[72:73]
	v_pk_fma_f32 v[8:9], v[56:57], v[74:75], v[8:9]
	v_add_f32_dpp v2, v2, v2 row_ror:8 row_mask:0xf bank_mask:0xf bound_ctrl:1
	v_add_f32_e32 v17, v8, v9
	v_pk_mul_f32 v[4:5], v[96:97], v[148:149] op_sel:[0,1] op_sel_hi:[1,1]
	v_add_f32_dpp v2, v2, v2 row_ror:4 row_mask:0xf bank_mask:0xf bound_ctrl:1
	v_pk_mul_f32 v[6:7], v[98:99], v[148:149] op_sel:[0,1] op_sel_hi:[1,1]
	v_pk_fma_f32 v[4:5], v[54:55], v[88:89], v[4:5]
	v_add_f32_dpp v2, v2, v2 row_ror:2 row_mask:0xf bank_mask:0xf bound_ctrl:1
	v_pk_fma_f32 v[6:7], v[56:57], v[90:91], v[6:7]
	ds_read_b128 v[140:143], v32 offset:14848
	v_add_f32_dpp v2, v2, v2 row_ror:1 row_mask:0xf bank_mask:0xf bound_ctrl:1
	v_pk_fma_f32 v[54:55], v[104:105], v[2:3], v[4:5] op_sel_hi:[1,0,1] neg_lo:[1,0,0] neg_hi:[1,0,0]
	v_pk_fma_f32 v[56:57], v[106:107], v[2:3], v[6:7] op_sel_hi:[1,0,1] neg_lo:[1,0,0] neg_hi:[1,0,0]
	ds_read_b128 v[136:139], v32 offset:14592
	ds_read_b128 v[128:131], v32 offset:14080
	ds_read_b128 v[144:147], v32 offset:15104
	ds_read_b128 v[132:135], v32 offset:14336
	s_waitcnt lgkmcnt(5)
	v_pk_mul_f32 v[156:157], v[54:55], v[120:121]
	v_pk_fma_f32 v[156:157], v[56:57], v[122:123], v[156:157]
	v_add_f32_e32 v2, v156, v157
	v_pk_mul_f32 v[8:9], v[54:55], v[92:93]
	v_pk_fma_f32 v[8:9], v[56:57], v[94:95], v[8:9]
	v_add_f32_dpp v2, v2, v2 row_ror:8 row_mask:0xf bank_mask:0xf bound_ctrl:1
	v_add_f32_e32 v18, v8, v9
	v_pk_mul_f32 v[4:5], v[116:117], v[150:151] op_sel_hi:[1,0]
	v_add_f32_dpp v2, v2, v2 row_ror:4 row_mask:0xf bank_mask:0xf bound_ctrl:1
	v_pk_mul_f32 v[6:7], v[118:119], v[150:151] op_sel_hi:[1,0]
	v_pk_fma_f32 v[4:5], v[54:55], v[108:109], v[4:5]
	v_add_f32_dpp v2, v2, v2 row_ror:2 row_mask:0xf bank_mask:0xf bound_ctrl:1
	v_pk_fma_f32 v[6:7], v[56:57], v[110:111], v[6:7]
	ds_read_b128 v[80:83], v32 offset:16128
	v_add_f32_dpp v2, v2, v2 row_ror:1 row_mask:0xf bank_mask:0xf bound_ctrl:1
	v_pk_fma_f32 v[54:55], v[124:125], v[2:3], v[4:5] op_sel_hi:[1,0,1] neg_lo:[1,0,0] neg_hi:[1,0,0]
	v_pk_fma_f32 v[56:57], v[126:127], v[2:3], v[6:7] op_sel_hi:[1,0,1] neg_lo:[1,0,0] neg_hi:[1,0,0]
	ds_read_b128 v[76:79], v32 offset:15872
	ds_read2_b32 v[152:153], v33 offset0:192 offset1:208
	ds_read_b128 v[68:71], v32 offset:15360
	ds_read_b128 v[84:87], v32 offset:16384
	ds_read_b128 v[72:75], v32 offset:15616
	s_waitcnt lgkmcnt(6)
	v_pk_mul_f32 v[156:157], v[54:55], v[140:141]
	v_pk_fma_f32 v[156:157], v[56:57], v[142:143], v[156:157]
	v_add_f32_e32 v2, v156, v157
	v_pk_mul_f32 v[8:9], v[54:55], v[112:113]
	v_pk_fma_f32 v[8:9], v[56:57], v[114:115], v[8:9]
	v_add_f32_dpp v2, v2, v2 row_ror:8 row_mask:0xf bank_mask:0xf bound_ctrl:1
	v_add_f32_e32 v19, v8, v9
	v_pk_mul_f32 v[4:5], v[136:137], v[150:151] op_sel:[0,1] op_sel_hi:[1,1]
	v_add_f32_dpp v2, v2, v2 row_ror:4 row_mask:0xf bank_mask:0xf bound_ctrl:1
	v_pk_mul_f32 v[6:7], v[138:139], v[150:151] op_sel:[0,1] op_sel_hi:[1,1]
	v_pk_fma_f32 v[4:5], v[54:55], v[128:129], v[4:5]
	v_add_f32_dpp v2, v2, v2 row_ror:2 row_mask:0xf bank_mask:0xf bound_ctrl:1
	v_pk_fma_f32 v[6:7], v[56:57], v[130:131], v[6:7]
	ds_read_b128 v[100:103], v32 offset:17408
	v_add_f32_dpp v2, v2, v2 row_ror:1 row_mask:0xf bank_mask:0xf bound_ctrl:1
	v_pk_fma_f32 v[54:55], v[144:145], v[2:3], v[4:5] op_sel_hi:[1,0,1] neg_lo:[1,0,0] neg_hi:[1,0,0]
	v_pk_fma_f32 v[56:57], v[146:147], v[2:3], v[6:7] op_sel_hi:[1,0,1] neg_lo:[1,0,0] neg_hi:[1,0,0]
	ds_read_b128 v[96:99], v32 offset:17152
	ds_read_b128 v[88:91], v32 offset:16640
	ds_read_b128 v[104:107], v32 offset:17664
	ds_read_b128 v[92:95], v32 offset:16896
	s_waitcnt lgkmcnt(5)
	v_pk_mul_f32 v[156:157], v[54:55], v[80:81]
	v_pk_fma_f32 v[156:157], v[56:57], v[82:83], v[156:157]
	v_add_f32_e32 v2, v156, v157
	v_pk_mul_f32 v[8:9], v[54:55], v[132:133]
	v_pk_fma_f32 v[8:9], v[56:57], v[134:135], v[8:9]
	v_add_f32_dpp v2, v2, v2 row_ror:8 row_mask:0xf bank_mask:0xf bound_ctrl:1
	v_add_f32_e32 v20, v8, v9
	v_pk_mul_f32 v[4:5], v[76:77], v[152:153] op_sel_hi:[1,0]
	v_add_f32_dpp v2, v2, v2 row_ror:4 row_mask:0xf bank_mask:0xf bound_ctrl:1
	v_pk_mul_f32 v[6:7], v[78:79], v[152:153] op_sel_hi:[1,0]
	v_pk_fma_f32 v[4:5], v[54:55], v[68:69], v[4:5]
	v_add_f32_dpp v2, v2, v2 row_ror:2 row_mask:0xf bank_mask:0xf bound_ctrl:1
	v_pk_fma_f32 v[6:7], v[56:57], v[70:71], v[6:7]
	ds_read_b128 v[120:123], v32 offset:18688
	v_add_f32_dpp v2, v2, v2 row_ror:1 row_mask:0xf bank_mask:0xf bound_ctrl:1
	v_pk_fma_f32 v[54:55], v[84:85], v[2:3], v[4:5] op_sel_hi:[1,0,1] neg_lo:[1,0,0] neg_hi:[1,0,0]
	v_pk_fma_f32 v[56:57], v[86:87], v[2:3], v[6:7] op_sel_hi:[1,0,1] neg_lo:[1,0,0] neg_hi:[1,0,0]
	ds_read_b128 v[116:119], v32 offset:18432
	ds_read2_b32 v[154:155], v33 offset0:224 offset1:240
	ds_read_b128 v[108:111], v32 offset:17920
	ds_read_b128 v[124:127], v32 offset:18944
	ds_read_b128 v[112:115], v32 offset:18176
	s_waitcnt lgkmcnt(6)
	v_pk_mul_f32 v[156:157], v[54:55], v[100:101]
	v_pk_fma_f32 v[156:157], v[56:57], v[102:103], v[156:157]
	v_add_f32_e32 v2, v156, v157
	v_pk_mul_f32 v[8:9], v[54:55], v[72:73]
	v_pk_fma_f32 v[8:9], v[56:57], v[74:75], v[8:9]
	v_add_f32_dpp v2, v2, v2 row_ror:8 row_mask:0xf bank_mask:0xf bound_ctrl:1
	v_add_f32_e32 v21, v8, v9
	v_pk_mul_f32 v[4:5], v[96:97], v[152:153] op_sel:[0,1] op_sel_hi:[1,1]
	v_add_f32_dpp v2, v2, v2 row_ror:4 row_mask:0xf bank_mask:0xf bound_ctrl:1
	v_pk_mul_f32 v[6:7], v[98:99], v[152:153] op_sel:[0,1] op_sel_hi:[1,1]
	v_pk_fma_f32 v[4:5], v[54:55], v[88:89], v[4:5]
	v_add_f32_dpp v2, v2, v2 row_ror:2 row_mask:0xf bank_mask:0xf bound_ctrl:1
	v_pk_fma_f32 v[6:7], v[56:57], v[90:91], v[6:7]
	ds_read_b128 v[140:143], v32 offset:19968
	v_add_f32_dpp v2, v2, v2 row_ror:1 row_mask:0xf bank_mask:0xf bound_ctrl:1
	v_pk_fma_f32 v[54:55], v[104:105], v[2:3], v[4:5] op_sel_hi:[1,0,1] neg_lo:[1,0,0] neg_hi:[1,0,0]
	v_pk_fma_f32 v[56:57], v[106:107], v[2:3], v[6:7] op_sel_hi:[1,0,1] neg_lo:[1,0,0] neg_hi:[1,0,0]
	ds_read_b128 v[136:139], v32 offset:19712
	ds_read_b128 v[128:131], v32 offset:19200
	ds_read_b128 v[144:147], v32 offset:20224
	ds_read_b128 v[132:135], v32 offset:19456
	s_waitcnt lgkmcnt(5)
	s_add_i32 s13, s36, s83
	s_add_i32 s13, s13, 1
	s_and_b32 s13, s13, 3
	s_lshl_b32 s12, s13, 2
	s_add_i32 s12, s12, 0x15000
	s_mul_i32 s13, s13, 0x5400
	v_mov_b32_e32 v26, s12
	v_add_u32_e32 v34, s13, v183
	v_add_u32_e32 v35, s13, v184
	v_add_u32_e32 v35, 0x5000, v35
	v_pk_mul_f32 v[156:157], v[54:55], v[120:121]
	v_pk_fma_f32 v[156:157], v[56:57], v[122:123], v[156:157]
	v_add_f32_e32 v2, v156, v157
	v_pk_mul_f32 v[8:9], v[54:55], v[92:93]
	v_pk_fma_f32 v[8:9], v[56:57], v[94:95], v[8:9]
	v_add_f32_dpp v2, v2, v2 row_ror:8 row_mask:0xf bank_mask:0xf bound_ctrl:1
	v_add_f32_e32 v22, v8, v9
	v_pk_mul_f32 v[4:5], v[116:117], v[154:155] op_sel_hi:[1,0]
	v_add_f32_dpp v2, v2, v2 row_ror:4 row_mask:0xf bank_mask:0xf bound_ctrl:1
	v_pk_mul_f32 v[6:7], v[118:119], v[154:155] op_sel_hi:[1,0]
	v_pk_fma_f32 v[4:5], v[54:55], v[108:109], v[4:5]
	v_add_f32_dpp v2, v2, v2 row_ror:2 row_mask:0xf bank_mask:0xf bound_ctrl:1
	v_pk_fma_f32 v[6:7], v[56:57], v[110:111], v[6:7]
	ds_read_b32 v25, v26
	v_add_f32_dpp v2, v2, v2 row_ror:1 row_mask:0xf bank_mask:0xf bound_ctrl:1
	v_pk_fma_f32 v[54:55], v[124:125], v[2:3], v[4:5] op_sel_hi:[1,0,1] neg_lo:[1,0,0] neg_hi:[1,0,0]
	v_pk_fma_f32 v[56:57], v[126:127], v[2:3], v[6:7] op_sel_hi:[1,0,1] neg_lo:[1,0,0] neg_hi:[1,0,0]
	ds_read_b128 v[80:83], v34 offset:768
	ds_read_b128 v[76:79], v34 offset:512
	ds_read2_b32 v[148:149], v35 offset0:0 offset1:16
	ds_read_b128 v[68:71], v34 offset:0
	ds_read_b128 v[84:87], v34 offset:1024
	ds_read_b128 v[72:75], v34 offset:256
	s_waitcnt lgkmcnt(7)
	v_pk_mul_f32 v[156:157], v[54:55], v[140:141]
	v_pk_fma_f32 v[156:157], v[56:57], v[142:143], v[156:157]
	v_add_f32_e32 v2, v156, v157
	v_pk_mul_f32 v[8:9], v[54:55], v[112:113]
	v_pk_fma_f32 v[8:9], v[56:57], v[114:115], v[8:9]
	v_add_f32_dpp v2, v2, v2 row_ror:8 row_mask:0xf bank_mask:0xf bound_ctrl:1
	v_add_f32_e32 v23, v8, v9
	v_pk_mul_f32 v[4:5], v[136:137], v[154:155] op_sel:[0,1] op_sel_hi:[1,1]
	v_add_f32_dpp v2, v2, v2 row_ror:4 row_mask:0xf bank_mask:0xf bound_ctrl:1
	v_pk_mul_f32 v[6:7], v[138:139], v[154:155] op_sel:[0,1] op_sel_hi:[1,1]
	v_pk_fma_f32 v[4:5], v[54:55], v[128:129], v[4:5]
	v_add_f32_dpp v2, v2, v2 row_ror:2 row_mask:0xf bank_mask:0xf bound_ctrl:1
	v_pk_fma_f32 v[6:7], v[56:57], v[130:131], v[6:7]
	ds_read_b128 v[100:103], v34 offset:2048
	v_add_f32_dpp v2, v2, v2 row_ror:1 row_mask:0xf bank_mask:0xf bound_ctrl:1
	v_pk_fma_f32 v[54:55], v[144:145], v[2:3], v[4:5] op_sel_hi:[1,0,1] neg_lo:[1,0,0] neg_hi:[1,0,0]
	v_pk_fma_f32 v[56:57], v[146:147], v[2:3], v[6:7] op_sel_hi:[1,0,1] neg_lo:[1,0,0] neg_hi:[1,0,0]
	ds_read_b128 v[96:99], v34 offset:1792
	ds_read_b128 v[88:91], v34 offset:1280
	ds_read_b128 v[104:107], v34 offset:2304
	ds_read_b128 v[92:95], v34 offset:1536
	v_pk_mul_f32 v[8:9], v[54:55], v[132:133]
	v_pk_fma_f32 v[8:9], v[56:57], v[134:135], v[8:9]
	v_add_f32_e32 v24, v8, v9
	v_add_f32_dpp v66, v66, v66 row_ror:8 row_mask:0xf bank_mask:0x3
	v_add_f32_dpp v66, v17, v17 row_ror:8 row_mask:0xf bank_mask:0xc
	v_add_f32_dpp v10, v10, v10 row_ror:8 row_mask:0xf bank_mask:0x3
	v_add_f32_dpp v10, v18, v18 row_ror:8 row_mask:0xf bank_mask:0xc
	v_add_f32_dpp v11, v11, v11 row_ror:8 row_mask:0xf bank_mask:0x3
	v_add_f32_dpp v11, v19, v19 row_ror:8 row_mask:0xf bank_mask:0xc
	v_add_f32_dpp v12, v12, v12 row_ror:8 row_mask:0xf bank_mask:0x3
	v_add_f32_dpp v12, v20, v20 row_ror:8 row_mask:0xf bank_mask:0xc
	v_add_f32_dpp v13, v13, v13 row_ror:8 row_mask:0xf bank_mask:0x3
	v_add_f32_dpp v13, v21, v21 row_ror:8 row_mask:0xf bank_mask:0xc
	v_add_f32_dpp v14, v14, v14 row_ror:8 row_mask:0xf bank_mask:0x3
	v_add_f32_dpp v14, v22, v22 row_ror:8 row_mask:0xf bank_mask:0xc
	v_add_f32_dpp v15, v15, v15 row_ror:8 row_mask:0xf bank_mask:0x3
	v_add_f32_dpp v15, v23, v23 row_ror:8 row_mask:0xf bank_mask:0xc
	v_add_f32_dpp v16, v16, v16 row_ror:8 row_mask:0xf bank_mask:0x3
	v_add_f32_dpp v16, v24, v24 row_ror:8 row_mask:0xf bank_mask:0xc
	v_add_f32_dpp v66, v66, v66 row_shl:4 row_mask:0xf bank_mask:0x5
	v_add_f32_dpp v66, v13, v13 row_shr:4 row_mask:0xf bank_mask:0xa
	v_add_f32_dpp v10, v10, v10 row_shl:4 row_mask:0xf bank_mask:0x5
	v_add_f32_dpp v10, v14, v14 row_shr:4 row_mask:0xf bank_mask:0xa
	v_add_f32_dpp v11, v11, v11 row_shl:4 row_mask:0xf bank_mask:0x5
	v_add_f32_dpp v11, v15, v15 row_shr:4 row_mask:0xf bank_mask:0xa
	v_add_f32_dpp v12, v12, v12 row_shl:4 row_mask:0xf bank_mask:0x5
	v_add_f32_dpp v12, v16, v16 row_shr:4 row_mask:0xf bank_mask:0xa
	v_add_f32_dpp v27, v66, v66 quad_perm:[2,3,0,1] row_mask:0xf bank_mask:0xf
	v_add_f32_dpp v28, v11, v11 quad_perm:[2,3,0,1] row_mask:0xf bank_mask:0xf
	v_cndmask_b32_e64 v66, v27, v28, s[78:79]
	v_add_f32_dpp v27, v10, v10 quad_perm:[2,3,0,1] row_mask:0xf bank_mask:0xf
	v_add_f32_dpp v28, v12, v12 quad_perm:[2,3,0,1] row_mask:0xf bank_mask:0xf
	v_cndmask_b32_e64 v10, v27, v28, s[78:79]
	s_add_i32 s13, s86, 0x15010
	v_mov_b32_e32 v26, s13
	s_mov_b64 s[12:13], exec
	s_mov_b64 exec, s[38:39]
	ds_add_u32 v26, v203
	s_mov_b64 exec, s[12:13]
	v_add_f32_dpp v27, v10, v10 quad_perm:[1,0,3,2] row_mask:0xf bank_mask:0xf
	v_add_f32_dpp v28, v66, v66 quad_perm:[1,0,3,2] row_mask:0xf bank_mask:0xf
	v_cndmask_b32_e64 v66, v28, v27, s[96:97]
	v_lshl_add_u32 v64, s36, 4, v59
	v_ashrrev_i32_e32 v65, 31, v64
	v_lshlrev_b64 v[64:65], 12, v[64:65]
	s_add_i32 s36, s36, 1
	v_lshl_add_u64 v[64:65], v[62:63], 0, v[64:65]
	s_waitcnt vmcnt(0)
	s_add_i32 s12, s36, -1
	v_mov_b32_e32 v30, s12
	s_mov_b64 s[12:13], exec
	s_mov_b64 exec, s[38:39]
	global_store_dword v29, v30, s[98:99]
	s_mov_b64 exec, s[12:13]

.Lsc_exit:
	s_waitcnt lgkmcnt(0)
	s_waitcnt vmcnt(0)
	v_mov_b32_e32 v30, s85
	s_mov_b64 s[12:13], exec
	s_mov_b64 exec, s[38:39]
	global_store_dword v29, v30, s[98:99]
	s_mov_b64 exec, s[12:13]

.LBB0_518:
.LBB0_519:
	s_setprio 0
	s_cmp_lg_u32 s82, 5
	s_cbranch_scc1 .Le_not5
	v_mov_b32_e32 v2, 0x15020
	s_mov_b64 s[0:1], exec
	s_mov_b64 exec, 1
	ds_add_u32 v2, v203
	s_mov_b64 exec, s[0:1]
	s_branch .Lw5_pre
.Lw5_back:
.Le_not5:
	s_cmp_lt_u32 s82, 6
	s_cbranch_scc1 .Ldc4_skip
	s_branch .Ldc4_entry

.Lpost_chunk:
	s_cmp_ge_u32 s64, s63
	s_cbranch_scc1 .Lpost_go

.Lpost_go:
	s_lshl_b32 s0, s39, 11
	s_lshl_b32 s1, s62, 4
	s_add_i32 s0, s0, s1
	v_add_u32_e32 v29, s0, v5
	v_lshl_add_u32 v47, v29, 12, v24
	v_lshl_add_u32 v48, v29, 11, v25
	v_lshl_add_u32 v49, v29, 6, v26
	v_lshl_add_u32 v50, v29, 12, v27
	global_load_dwordx4 v[30:33], v47, s[40:41] sc1
	global_load_dwordx4 v[34:37], v47, s[40:41] offset:16 sc1
	global_load_dwordx4 v[38:41], v48, s[42:43]
	global_load_dwordx4 v[42:45], v48, s[44:45]
	global_load_dword v46, v49, s[46:47]
	v_add_u32_e32 v87, 0x8000, v47
	v_add_u32_e32 v88, 0x4000, v48
	v_add_u32_e32 v89, 0x200, v49
	v_add_u32_e32 v90, 0x8000, v50
	global_load_dwordx4 v[70:73], v87, s[40:41] sc1
	global_load_dwordx4 v[74:77], v87, s[40:41] offset:16 sc1
	global_load_dwordx4 v[78:81], v88, s[42:43]
	global_load_dwordx4 v[82:85], v88, s[44:45]
	global_load_dword v86, v89, s[46:47]
	s_waitcnt vmcnt(5)
	v_add_f32_e32 v51, v30, v31
	v_add_f32_e32 v51, v32, v51
	v_add_f32_e32 v51, v33, v51
	v_add_f32_e32 v51, v34, v51
	v_add_f32_e32 v51, v35, v51
	v_add_f32_e32 v51, v36, v51
	v_add_f32_e32 v51, v37, v51
	s_nop 1
	v_add_f32_dpp v51, v51, v51 quad_perm:[1,0,3,2] row_mask:0xf bank_mask:0xf
	s_nop 1
	v_add_f32_dpp v51, v51, v51 quad_perm:[2,3,0,1] row_mask:0xf bank_mask:0xf
	s_nop 1
	v_add_f32_dpp v51, v51, v51 row_half_mirror row_mask:0xf bank_mask:0xf
	v_mul_f32_e32 v52, s58, v51
	v_sub_f32_e32 v30, v30, v52
	v_sub_f32_e32 v31, v31, v52
	v_sub_f32_e32 v32, v32, v52
	v_sub_f32_e32 v33, v33, v52
	v_sub_f32_e32 v34, v34, v52
	v_sub_f32_e32 v35, v35, v52
	v_sub_f32_e32 v36, v36, v52
	v_sub_f32_e32 v37, v37, v52
	v_mul_f32_e32 v62, v30, v30
	v_mul_f32_e32 v53, v31, v31
	v_add_f32_e32 v62, v53, v62
	v_mul_f32_e32 v53, v32, v32
	v_add_f32_e32 v62, v53, v62
	v_mul_f32_e32 v53, v33, v33
	v_add_f32_e32 v62, v53, v62
	v_mul_f32_e32 v53, v34, v34
	v_add_f32_e32 v62, v53, v62
	v_mul_f32_e32 v53, v35, v35
	v_add_f32_e32 v62, v53, v62
	v_mul_f32_e32 v53, v36, v36
	v_add_f32_e32 v62, v53, v62
	v_mul_f32_e32 v53, v37, v37
	v_add_f32_e32 v62, v53, v62
	s_nop 1
	v_add_f32_dpp v62, v62, v62 quad_perm:[1,0,3,2] row_mask:0xf bank_mask:0xf
	s_nop 1
	v_add_f32_dpp v62, v62, v62 quad_perm:[2,3,0,1] row_mask:0xf bank_mask:0xf
	s_nop 1
	v_add_f32_dpp v62, v62, v62 row_half_mirror row_mask:0xf bank_mask:0xf
	v_fma_f32 v62, v62, s58, v162
	v_mul_f32_e32 v53, 0x4b800000, v62
	v_cmp_gt_f32_e32 vcc, s5, v62
	s_nop 1
	v_cndmask_b32_e32 v53, v62, v53, vcc
	v_rsq_f32_e32 v53, v53
	s_nop 0
	v_mul_f32_e32 v52, 0x45800000, v53
	v_cndmask_b32_e32 v52, v53, v52, vcc
	v_mul_f32_e32 v30, v30, v52
	v_fma_f32 v30, v8, v30, v16
	v_lshlrev_b32_e32 v53, 16, v38
	v_fma_f32 v30, v46, v53, v30
	v_lshlrev_b32_e32 v53, 16, v42
	v_mul_f32_e32 v30, v30, v53
	v_mul_f32_e32 v31, v31, v52
	v_fma_f32 v31, v9, v31, v17
	v_and_b32_e32 v53, 0xffff0000, v38
	v_fma_f32 v31, v46, v53, v31
	v_and_b32_e32 v53, 0xffff0000, v42
	v_mul_f32_e32 v31, v31, v53
	v_mul_f32_e32 v32, v32, v52
	v_fma_f32 v32, v10, v32, v18
	v_lshlrev_b32_e32 v53, 16, v39
	v_fma_f32 v32, v46, v53, v32
	v_lshlrev_b32_e32 v53, 16, v43
	v_mul_f32_e32 v32, v32, v53
	v_mul_f32_e32 v33, v33, v52
	v_fma_f32 v33, v11, v33, v19
	v_and_b32_e32 v53, 0xffff0000, v39
	v_fma_f32 v33, v46, v53, v33
	v_and_b32_e32 v53, 0xffff0000, v43
	v_mul_f32_e32 v33, v33, v53
	v_mul_f32_e32 v34, v34, v52
	v_fma_f32 v34, v12, v34, v20
	v_lshlrev_b32_e32 v53, 16, v40
	v_fma_f32 v34, v46, v53, v34
	v_lshlrev_b32_e32 v53, 16, v44
	v_mul_f32_e32 v34, v34, v53
	v_mul_f32_e32 v35, v35, v52
	v_fma_f32 v35, v13, v35, v21
	v_and_b32_e32 v53, 0xffff0000, v40
	v_fma_f32 v35, v46, v53, v35
	v_and_b32_e32 v53, 0xffff0000, v44
	v_mul_f32_e32 v35, v35, v53
	v_mul_f32_e32 v36, v36, v52
	v_fma_f32 v36, v14, v36, v22
	v_lshlrev_b32_e32 v53, 16, v41
	v_fma_f32 v36, v46, v53, v36
	v_lshlrev_b32_e32 v53, 16, v45
	v_mul_f32_e32 v36, v36, v53
	v_mul_f32_e32 v37, v37, v52
	v_fma_f32 v37, v15, v37, v23
	v_and_b32_e32 v53, 0xffff0000, v41
	v_fma_f32 v37, v46, v53, v37
	v_and_b32_e32 v53, 0xffff0000, v45
	v_mul_f32_e32 v37, v37, v53
	v_cvt_pk_bf16_f32 v54, v30, v31
	v_cvt_pk_bf16_f32 v55, v32, v33
	v_cvt_pk_bf16_f32 v56, v34, v35
	v_cvt_pk_bf16_f32 v57, v36, v37
	global_store_dwordx4 v50, v[54:57], s[48:49]
	s_waitcnt vmcnt(0)
	v_add_f32_e32 v91, v70, v71
	v_add_f32_e32 v91, v72, v91
	v_add_f32_e32 v91, v73, v91
	v_add_f32_e32 v91, v74, v91
	v_add_f32_e32 v91, v75, v91
	v_add_f32_e32 v91, v76, v91
	v_add_f32_e32 v91, v77, v91
	s_nop 1
	v_add_f32_dpp v91, v91, v91 quad_perm:[1,0,3,2] row_mask:0xf bank_mask:0xf
	s_nop 1
	v_add_f32_dpp v91, v91, v91 quad_perm:[2,3,0,1] row_mask:0xf bank_mask:0xf
	s_nop 1
	v_add_f32_dpp v91, v91, v91 row_half_mirror row_mask:0xf bank_mask:0xf
	v_mul_f32_e32 v92, s58, v91
	v_sub_f32_e32 v70, v70, v92
	v_sub_f32_e32 v71, v71, v92
	v_sub_f32_e32 v72, v72, v92
	v_sub_f32_e32 v73, v73, v92
	v_sub_f32_e32 v74, v74, v92
	v_sub_f32_e32 v75, v75, v92
	v_sub_f32_e32 v76, v76, v92
	v_sub_f32_e32 v77, v77, v92
	v_mul_f32_e32 v102, v70, v70
	v_mul_f32_e32 v93, v71, v71
	v_add_f32_e32 v102, v93, v102
	v_mul_f32_e32 v93, v72, v72
	v_add_f32_e32 v102, v93, v102
	v_mul_f32_e32 v93, v73, v73
	v_add_f32_e32 v102, v93, v102
	v_mul_f32_e32 v93, v74, v74
	v_add_f32_e32 v102, v93, v102
	v_mul_f32_e32 v93, v75, v75
	v_add_f32_e32 v102, v93, v102
	v_mul_f32_e32 v93, v76, v76
	v_add_f32_e32 v102, v93, v102
	v_mul_f32_e32 v93, v77, v77
	v_add_f32_e32 v102, v93, v102
	s_nop 1
	v_add_f32_dpp v102, v102, v102 quad_perm:[1,0,3,2] row_mask:0xf bank_mask:0xf
	s_nop 1
	v_add_f32_dpp v102, v102, v102 quad_perm:[2,3,0,1] row_mask:0xf bank_mask:0xf
	s_nop 1
	v_add_f32_dpp v102, v102, v102 row_half_mirror row_mask:0xf bank_mask:0xf
	v_fma_f32 v102, v102, s58, v162
	v_mul_f32_e32 v93, 0x4b800000, v102
	v_cmp_gt_f32_e32 vcc, s5, v102
	s_nop 1
	v_cndmask_b32_e32 v93, v102, v93, vcc
	v_rsq_f32_e32 v93, v93
	s_nop 0
	v_mul_f32_e32 v92, 0x45800000, v93
	v_cndmask_b32_e32 v92, v93, v92, vcc
	v_mul_f32_e32 v70, v70, v92
	v_fma_f32 v70, v8, v70, v16
	v_lshlrev_b32_e32 v93, 16, v78
	v_fma_f32 v70, v86, v93, v70
	v_lshlrev_b32_e32 v93, 16, v82
	v_mul_f32_e32 v70, v70, v93
	v_mul_f32_e32 v71, v71, v92
	v_fma_f32 v71, v9, v71, v17
	v_and_b32_e32 v93, 0xffff0000, v78
	v_fma_f32 v71, v86, v93, v71
	v_and_b32_e32 v93, 0xffff0000, v82
	v_mul_f32_e32 v71, v71, v93
	v_mul_f32_e32 v72, v72, v92
	v_fma_f32 v72, v10, v72, v18
	v_lshlrev_b32_e32 v93, 16, v79
	v_fma_f32 v72, v86, v93, v72
	v_lshlrev_b32_e32 v93, 16, v83
	v_mul_f32_e32 v72, v72, v93
	v_mul_f32_e32 v73, v73, v92
	v_fma_f32 v73, v11, v73, v19
	v_and_b32_e32 v93, 0xffff0000, v79
	v_fma_f32 v73, v86, v93, v73
	v_and_b32_e32 v93, 0xffff0000, v83
	v_mul_f32_e32 v73, v73, v93
	v_mul_f32_e32 v74, v74, v92
	v_fma_f32 v74, v12, v74, v20
	v_lshlrev_b32_e32 v93, 16, v80
	v_fma_f32 v74, v86, v93, v74
	v_lshlrev_b32_e32 v93, 16, v84
	v_mul_f32_e32 v74, v74, v93
	v_mul_f32_e32 v75, v75, v92
	v_fma_f32 v75, v13, v75, v21
	v_and_b32_e32 v93, 0xffff0000, v80
	v_fma_f32 v75, v86, v93, v75
	v_and_b32_e32 v93, 0xffff0000, v84
	v_mul_f32_e32 v75, v75, v93
	v_mul_f32_e32 v76, v76, v92
	v_fma_f32 v76, v14, v76, v22
	v_lshlrev_b32_e32 v93, 16, v81
	v_fma_f32 v76, v86, v93, v76
	v_lshlrev_b32_e32 v93, 16, v85
	v_mul_f32_e32 v76, v76, v93
	v_mul_f32_e32 v77, v77, v92
	v_fma_f32 v77, v15, v77, v23
	v_and_b32_e32 v93, 0xffff0000, v81
	v_fma_f32 v77, v86, v93, v77
	v_and_b32_e32 v93, 0xffff0000, v85
	v_mul_f32_e32 v77, v77, v93
	v_cvt_pk_bf16_f32 v94, v70, v71
	v_cvt_pk_bf16_f32 v95, v72, v73
	v_cvt_pk_bf16_f32 v96, v74, v75
	v_cvt_pk_bf16_f32 v97, v76, v77
	global_store_dwordx4 v90, v[94:97], s[48:49]
	s_add_i32 s59, s59, 3
	s_cmp_lt_u32 s59, 32
	s_cbranch_scc1 .Lpost_loop
	s_cmp_lg_u32 s12, 0
	s_cbranch_scc1 .Lpost_done
	s_cmp_gt_u32 s13, 1
	s_cbranch_scc1 .Lpost_done
	s_mov_b32 s12, 1
	s_lshl_b32 s0, s13, 12
	s_add_u32 s0, s0, 0x1000
	s_add_u32 s50, s50, s0
	s_addc_u32 s51, s51, 0
	s_mov_b32 s64, 0
	s_lshl_b32 s0, s13, 2
	s_add_i32 s62, s39, s0
	s_mov_b32 s39, 4
	s_mov_b32 s63, 1
	s_mov_b32 s59, 64
	s_branch .Lpost_chunk

.Lw5_pre:
	s_mov_b64 exec, -1
	v_readlane_b32 s12, v253, 60
	v_readlane_b32 s13, v253, 61
	v_readlane_b32 s40, v255, 31
	v_readlane_b32 s41, v255, 32
	v_readlane_b32 s36, v255, 13
	s_nop 4
	s_lshl_b32 s38, s36, 12
	v_lshl_add_u32 v2, v161, 4, s38
	global_load_dwordx4 v[4:7], v2, s[12:13]
	global_load_dwordx4 v[8:11], v2, s[12:13] offset:1024
	global_load_dwordx4 v[12:15], v2, s[12:13] offset:2048
	global_load_dwordx4 v[16:19], v2, s[12:13] offset:3072
	s_waitcnt vmcnt(0)
	global_store_dwordx4 v2, v[4:7], s[40:41]
	global_store_dwordx4 v2, v[8:11], s[40:41] offset:1024
	global_store_dwordx4 v2, v[12:15], s[40:41] offset:2048
	global_store_dwordx4 v2, v[16:19], s[40:41] offset:3072
	v_mov_b32_e32 v24, v161
	v_mov_b32_e32 v28, s36
	v_lshlrev_b32_e32 v27, 6, v28
	v_lshlrev_b32_e32 v25, 4, v28
	s_mov_b64 s[38:39], 0
	s_branch .Lnv_440
.Lnv_439:
	s_or_b64 exec, exec, s[12:13]
	s_movk_i32 s12, 0x3c0
	v_and_or_b32 v3, v27, s12, v24
	v_lshlrev_b32_e32 v0, 2, v3
	v_lshl_add_u64 v[22:23], v[4:5], 0, v[0:1]
	v_mul_u32_u24_e32 v0, 0x2100, v3
	v_readlane_b32 s12, v250, 28
	v_lshlrev_b32_e32 v0, 1, v0
	v_readlane_b32 s13, v250, 29
	v_ashrrev_i32_e32 v3, 31, v2
	s_nop 0
	v_lshl_add_u64 v[4:5], s[12:13], 0, v[0:1]
	v_lshl_add_u64 v[14:15], v[2:3], 1, v[4:5]
	global_load_dwordx4 v[18:21], v[14:15], off offset:48
	global_load_dwordx4 v[30:33], v[14:15], off offset:32
	global_load_dwordx4 v[34:37], v[14:15], off offset:16
	global_load_dwordx4 v[38:41], v[14:15], off
	global_load_dwordx4 v[2:5], v[14:15], off offset:112
	global_load_dwordx4 v[6:9], v[14:15], off offset:96
	global_load_dwordx4 v[10:13], v[14:15], off offset:80
	s_nop 0
	global_load_dwordx4 v[14:17], v[14:15], off offset:64
	s_movk_i32 s12, 0x2000
	s_waitcnt vmcnt(0)
	v_lshlrev_b32_e32 v0, 16, v38
	v_and_b32_e32 v29, 0xffff0000, v38
	v_add_co_u32_e32 v38, vcc, s12, v22
	v_lshlrev_b32_e32 v42, 16, v39
	v_and_b32_e32 v43, 0xffff0000, v39
	v_addc_co_u32_e32 v39, vcc, 0, v23, vcc
	s_movk_i32 s12, 0x4000
	global_store_dword v[22:23], v0, off
	global_store_dword v[38:39], v29, off offset:-4096
	global_store_dword v[38:39], v42, off
	v_add_co_u32_e32 v38, vcc, s12, v22
	s_movk_i32 s12, 0x6000
	s_nop 0
	v_addc_co_u32_e32 v39, vcc, 0, v23, vcc
	v_lshlrev_b32_e32 v44, 16, v40
	global_store_dword v[38:39], v43, off offset:-4096
	global_store_dword v[38:39], v44, off
	v_add_co_u32_e32 v38, vcc, s12, v22
	v_and_b32_e32 v40, 0xffff0000, v40
	s_nop 0
	v_addc_co_u32_e32 v39, vcc, 0, v23, vcc
	s_mov_b32 s12, 0x8000
	v_lshlrev_b32_e32 v45, 16, v41
	global_store_dword v[38:39], v40, off offset:-4096
	global_store_dword v[38:39], v45, off
	v_add_co_u32_e32 v38, vcc, s12, v22
	v_and_b32_e32 v41, 0xffff0000, v41
	s_nop 0
	v_addc_co_u32_e32 v39, vcc, 0, v23, vcc
	global_store_dword v[38:39], v41, off offset:-4096
	s_mov_b32 s12, 0xa000
	v_lshlrev_b32_e32 v0, 16, v34
	v_and_b32_e32 v29, 0xffff0000, v34
	v_add_co_u32_e32 v34, vcc, s12, v22
	v_lshlrev_b32_e32 v40, 16, v35
	v_and_b32_e32 v41, 0xffff0000, v35
	v_addc_co_u32_e32 v35, vcc, 0, v23, vcc
	s_mov_b32 s12, 0xc000
	global_store_dword v[38:39], v0, off
	global_store_dword v[34:35], v29, off offset:-4096
	global_store_dword v[34:35], v40, off
	v_add_co_u32_e32 v34, vcc, s12, v22
	s_mov_b32 s12, 0xe000
	s_nop 0
	v_addc_co_u32_e32 v35, vcc, 0, v23, vcc
	v_lshlrev_b32_e32 v42, 16, v36
	global_store_dword v[34:35], v41, off offset:-4096
	global_store_dword v[34:35], v42, off
	v_add_co_u32_e32 v34, vcc, s12, v22
	v_and_b32_e32 v36, 0xffff0000, v36
	s_nop 0
	v_addc_co_u32_e32 v35, vcc, 0, v23, vcc
	s_mov_b32 s12, 0x10000
	v_lshlrev_b32_e32 v43, 16, v37
	global_store_dword v[34:35], v36, off offset:-4096
	global_store_dword v[34:35], v43, off
	v_add_co_u32_e32 v34, vcc, s12, v22
	v_and_b32_e32 v37, 0xffff0000, v37
	s_nop 0
	v_addc_co_u32_e32 v35, vcc, 0, v23, vcc
	global_store_dword v[34:35], v37, off offset:-4096
	s_mov_b32 s12, 0x12000
	v_lshlrev_b32_e32 v0, 16, v30
	v_and_b32_e32 v29, 0xffff0000, v30
	v_add_co_u32_e32 v30, vcc, s12, v22
	v_lshlrev_b32_e32 v36, 16, v31
	v_and_b32_e32 v37, 0xffff0000, v31
	v_addc_co_u32_e32 v31, vcc, 0, v23, vcc
	s_mov_b32 s12, 0x14000
	global_store_dword v[34:35], v0, off
	global_store_dword v[30:31], v29, off offset:-4096
	global_store_dword v[30:31], v36, off
	v_add_co_u32_e32 v30, vcc, s12, v22
	s_mov_b32 s12, 0x16000
	s_nop 0
	v_addc_co_u32_e32 v31, vcc, 0, v23, vcc
	v_lshlrev_b32_e32 v38, 16, v32
	global_store_dword v[30:31], v37, off offset:-4096
	global_store_dword v[30:31], v38, off
	v_add_co_u32_e32 v30, vcc, s12, v22
	v_and_b32_e32 v32, 0xffff0000, v32
	s_nop 0
	v_addc_co_u32_e32 v31, vcc, 0, v23, vcc
	s_mov_b32 s12, 0x18000
	v_lshlrev_b32_e32 v39, 16, v33
	global_store_dword v[30:31], v32, off offset:-4096
	global_store_dword v[30:31], v39, off
	v_add_co_u32_e32 v30, vcc, s12, v22
	v_and_b32_e32 v33, 0xffff0000, v33
	s_nop 0
	v_addc_co_u32_e32 v31, vcc, 0, v23, vcc
	global_store_dword v[30:31], v33, off offset:-4096
	s_mov_b32 s12, 0x1a000
	v_lshlrev_b32_e32 v0, 16, v18
	v_and_b32_e32 v29, 0xffff0000, v18
	v_add_co_u32_e32 v18, vcc, s12, v22
	v_lshlrev_b32_e32 v32, 16, v19
	v_and_b32_e32 v33, 0xffff0000, v19
	v_addc_co_u32_e32 v19, vcc, 0, v23, vcc
	s_mov_b32 s12, 0x1c000
	global_store_dword v[30:31], v0, off
	global_store_dword v[18:19], v29, off offset:-4096
	global_store_dword v[18:19], v32, off
	v_add_co_u32_e32 v18, vcc, s12, v22
	s_mov_b32 s12, 0x1e000
	s_nop 0
	v_addc_co_u32_e32 v19, vcc, 0, v23, vcc
	v_lshlrev_b32_e32 v34, 16, v20
	global_store_dword v[18:19], v33, off offset:-4096
	global_store_dword v[18:19], v34, off
	v_add_co_u32_e32 v18, vcc, s12, v22
	v_and_b32_e32 v20, 0xffff0000, v20
	s_nop 0
	v_addc_co_u32_e32 v19, vcc, 0, v23, vcc
	s_mov_b32 s12, 0x20000
	v_lshlrev_b32_e32 v35, 16, v21
	global_store_dword v[18:19], v20, off offset:-4096
	global_store_dword v[18:19], v35, off
	v_add_co_u32_e32 v18, vcc, s12, v22
	v_and_b32_e32 v21, 0xffff0000, v21
	s_nop 0
	v_addc_co_u32_e32 v19, vcc, 0, v23, vcc
	global_store_dword v[18:19], v21, off offset:-4096
	s_mov_b32 s12, 0x22000
	v_lshlrev_b32_e32 v0, 16, v14
	v_and_b32_e32 v20, 0xffff0000, v14
	v_add_co_u32_e32 v14, vcc, s12, v22
	v_lshlrev_b32_e32 v21, 16, v15
	v_and_b32_e32 v29, 0xffff0000, v15
	v_addc_co_u32_e32 v15, vcc, 0, v23, vcc
	s_mov_b32 s12, 0x24000
	global_store_dword v[18:19], v0, off
	global_store_dword v[14:15], v20, off offset:-4096
	global_store_dword v[14:15], v21, off
	v_add_co_u32_e32 v14, vcc, s12, v22
	s_mov_b32 s12, 0x26000
	s_nop 0
	v_addc_co_u32_e32 v15, vcc, 0, v23, vcc
	v_lshlrev_b32_e32 v30, 16, v16
	global_store_dword v[14:15], v29, off offset:-4096
	global_store_dword v[14:15], v30, off
	v_add_co_u32_e32 v14, vcc, s12, v22
	v_and_b32_e32 v16, 0xffff0000, v16
	s_nop 0
	v_addc_co_u32_e32 v15, vcc, 0, v23, vcc
	s_mov_b32 s12, 0x28000
	v_lshlrev_b32_e32 v31, 16, v17
	global_store_dword v[14:15], v16, off offset:-4096
	global_store_dword v[14:15], v31, off
	v_add_co_u32_e32 v14, vcc, s12, v22
	v_and_b32_e32 v17, 0xffff0000, v17
	s_nop 0
	v_addc_co_u32_e32 v15, vcc, 0, v23, vcc
	global_store_dword v[14:15], v17, off offset:-4096
	s_mov_b32 s12, 0x2a000
	v_lshlrev_b32_e32 v0, 16, v10
	v_and_b32_e32 v16, 0xffff0000, v10
	v_add_co_u32_e32 v10, vcc, s12, v22
	v_lshlrev_b32_e32 v17, 16, v11
	v_and_b32_e32 v18, 0xffff0000, v11
	v_addc_co_u32_e32 v11, vcc, 0, v23, vcc
	s_mov_b32 s12, 0x2c000
	global_store_dword v[14:15], v0, off
	global_store_dword v[10:11], v16, off offset:-4096
	global_store_dword v[10:11], v17, off
	v_add_co_u32_e32 v10, vcc, s12, v22
	s_mov_b32 s12, 0x2e000
	s_nop 0
	v_addc_co_u32_e32 v11, vcc, 0, v23, vcc
	v_lshlrev_b32_e32 v19, 16, v12
	global_store_dword v[10:11], v18, off offset:-4096
	global_store_dword v[10:11], v19, off
	v_add_co_u32_e32 v10, vcc, s12, v22
	v_and_b32_e32 v12, 0xffff0000, v12
	s_nop 0
	v_addc_co_u32_e32 v11, vcc, 0, v23, vcc
	s_mov_b32 s12, 0x30000
	v_lshlrev_b32_e32 v20, 16, v13
	global_store_dword v[10:11], v12, off offset:-4096
	global_store_dword v[10:11], v20, off
	v_add_co_u32_e32 v10, vcc, s12, v22
	v_and_b32_e32 v13, 0xffff0000, v13
	s_nop 0
	v_addc_co_u32_e32 v11, vcc, 0, v23, vcc
	global_store_dword v[10:11], v13, off offset:-4096
	s_mov_b32 s12, 0x32000
	v_lshlrev_b32_e32 v0, 16, v6
	v_and_b32_e32 v12, 0xffff0000, v6
	v_add_co_u32_e32 v6, vcc, s12, v22
	v_lshlrev_b32_e32 v13, 16, v7
	v_and_b32_e32 v14, 0xffff0000, v7
	v_addc_co_u32_e32 v7, vcc, 0, v23, vcc
	s_mov_b32 s12, 0x34000
	global_store_dword v[10:11], v0, off
	global_store_dword v[6:7], v12, off offset:-4096
	global_store_dword v[6:7], v13, off
	v_add_co_u32_e32 v6, vcc, s12, v22
	s_mov_b32 s12, 0x36000
	s_nop 0
	v_addc_co_u32_e32 v7, vcc, 0, v23, vcc
	v_lshlrev_b32_e32 v15, 16, v8
	global_store_dword v[6:7], v14, off offset:-4096
	global_store_dword v[6:7], v15, off
	v_add_co_u32_e32 v6, vcc, s12, v22
	v_and_b32_e32 v8, 0xffff0000, v8
	s_nop 0
	v_addc_co_u32_e32 v7, vcc, 0, v23, vcc
	s_mov_b32 s12, 0x38000
	v_lshlrev_b32_e32 v16, 16, v9
	global_store_dword v[6:7], v8, off offset:-4096
	global_store_dword v[6:7], v16, off
	v_add_co_u32_e32 v6, vcc, s12, v22
	v_and_b32_e32 v9, 0xffff0000, v9
	s_nop 0
	v_addc_co_u32_e32 v7, vcc, 0, v23, vcc
	global_store_dword v[6:7], v9, off offset:-4096
	s_mov_b32 s12, 0x3a000
	v_lshlrev_b32_e32 v0, 16, v2
	v_and_b32_e32 v8, 0xffff0000, v2
	v_add_co_u32_e32 v2, vcc, s12, v22
	v_lshlrev_b32_e32 v9, 16, v3
	v_and_b32_e32 v10, 0xffff0000, v3
	v_addc_co_u32_e32 v3, vcc, 0, v23, vcc
	s_mov_b32 s12, 0x3c000
	global_store_dword v[6:7], v0, off
	global_store_dword v[2:3], v8, off offset:-4096
	global_store_dword v[2:3], v9, off
	v_add_co_u32_e32 v2, vcc, s12, v22
	s_mov_b32 s12, 0x3d000
	s_nop 0
	v_addc_co_u32_e32 v3, vcc, 0, v23, vcc
	v_lshlrev_b32_e32 v11, 16, v4
	global_store_dword v[2:3], v10, off offset:-4096
	global_store_dword v[2:3], v11, off
	v_add_co_u32_e32 v2, vcc, s12, v22
	v_and_b32_e32 v4, 0xffff0000, v4
	s_nop 0
	v_addc_co_u32_e32 v3, vcc, 0, v23, vcc
	global_store_dword v[2:3], v4, off
	v_add_co_u32_e32 v2, vcc, 0x3e000, v22
	v_lshlrev_b32_e32 v12, 16, v5
	s_nop 0
	v_addc_co_u32_e32 v3, vcc, 0, v23, vcc
	global_store_dword v[2:3], v12, off
	v_add_co_u32_e32 v2, vcc, 0x3f000, v22
	v_and_b32_e32 v5, 0xffff0000, v5
	s_nop 0
	v_addc_co_u32_e32 v3, vcc, 0, v23, vcc
	global_store_dword v[2:3], v5, off
	v_add_u32_e32 v28, 0x100, v28
	v_add_u32_e32 v27, 0x4000, v27
	v_add_u32_e32 v25, 0x1000, v25
	s_movk_i32 s12, 0x21f
	v_cmp_lt_i32_e32 vcc, s12, v28
	s_or_b64 s[38:39], vcc, s[38:39]
	s_andn2_b64 exec, exec, s[38:39]
	s_cbranch_execz .Lnv_done

.Lnv_done:
	s_mov_b64 exec, -1
	s_branch .Lw5_back

.LBB0_556:
	s_or_b64 exec, exec, s[0:1]
	v_cmp_gt_u32_e32 vcc, 12, v166
	s_and_saveexec_b64 s[0:1], vcc
	v_readlane_b32 s12, v255, 13
	s_add_u32 s38, s24, 0x4a80000
	s_addc_u32 s39, s25, 0
	s_mul_i32 s12, s12, 48
	v_lshl_add_u32 v2, v166, 2, s12
	global_store_dword v2, v1, s[38:39]
	s_or_b64 exec, exec, s[0:1]
	v_readlane_b32 s0, v250, 4
	v_readlane_b32 s1, v250, 5
	s_andn2_b64 vcc, exec, s[0:1]
	s_mov_b32 s66, 0x3d000
	s_movk_i32 s67, 0x207f
	s_movk_i32 s68, 0x7f
	s_cbranch_vccnz .LBB0_583
	v_readlane_b32 s0, v250, 46
	v_readlane_b32 s1, v250, 47
	s_andn2_b64 vcc, exec, s[0:1]
	v_readfirstlane_b32 s52, v166
	s_cbranch_vccnz .LBB0_582
	v_readlane_b32 s12, v250, 48
	v_readlane_b32 s13, v250, 49
	v_readlane_b32 s38, v254, 20
	v_readlane_b32 s46, v250, 52
	s_mov_b64 s[0:1], 0x6917000
	s_mov_b32 s62, 1
	s_andn2_b64 vcc, exec, s[12:13]
	v_readlane_b32 s39, v254, 21
	s_mov_b32 s61, s38
	v_readlane_b32 s58, v250, 51
	v_readlane_b32 s47, v250, 53
	s_cbranch_vccnz .LBB0_560
	v_readlane_b32 s38, v253, 32
	v_readlane_b32 s12, v253, 28
	v_readlane_b32 s46, v253, 30
	s_mov_b64 s[0:1], 0x5017000
	s_mov_b32 s62, 0
	v_readlane_b32 s39, v253, 33
	s_mov_b32 s61, s38
	s_mov_b32 s58, s12
	v_readlane_b32 s47, v253, 31
	v_readlane_b32 s13, v253, 29
